# v49 + LDS read balance: B(k1,half1) fragments read in phase 2's load segment into spare registers (12/12 reads in phases 2/3 instead of 8/16); phase-1 wait certifies the B(k1) stage one phase earlier
# baseline (speedup 1.0000x reference)
; #define PG8_WAIT_V(n) asm volatile("s_waitcnt vmcnt(" #n ")" ::: "memory")
; template <class Epi, bool ALIGN_EPI, bool SP2, class Hook>
; __device__ __forceinline__ void gemm_phase(LAS unsigned char* lds, const Gemm g, const StaticOrder& S, const Epi& E, Acc& acc, const bool fresh, const Hook& H, const int wave_id) {
;     ...
;             const bool last = (t == nt - 2);
;             const Src a1 = cA + (size_t)(t + 1) * kstep;
;             const Src a2 = last ? nA : cA + (size_t)(t + 2) * kstep, b2 = last ? nB : cB + (size_t)(t + 2) * kstep;
;             const Src a3 = a2 + kstep, b3 = b2 + kstep;
;             if (last && has_next) H(nxt);
;             if constexpr (SP2) {
;             PG8_TRIP_SP2(PG8_WAIT_V(8));
.LBB0_391:
	s_add_i32 s100, s56, 0xfffc0000
	v_add_u32_e32 v150, 0x10000, v148
	v_add_u32_e32 v151, 0x14000, v148
	ds_read_b128 v[132:135], v150
	ds_read_b128 v[136:139], v150 offset:1024
	ds_read_b128 v[140:143], v150 offset:2048
	ds_read_b128 v[152:155], v150 offset:3072
	ds_read_b128 v[156:159], v151
	ds_read_b128 v[160:163], v151 offset:1024
	ds_read_b128 v[164:167], v151 offset:2048
	ds_read_b128 v[168:171], v151 offset:3072
	s_mov_b32 m0, s41
	s_nop 0
	buffer_load_dwordx4 v144, s[8:11], s100 offen lds
	s_mov_b32 m0, s33
	s_nop 0
	buffer_load_dwordx4 v146, s[8:11], s100 offen lds
	s_mov_b32 m0, s45
	ds_read_b128 v[172:175], v149
	ds_read_b128 v[176:179], v149 offset:1024
	ds_read_b128 v[180:183], v149 offset:2048
	ds_read_b128 v[184:187], v149 offset:3072
	ds_read_b128 v[188:191], v149 offset:4096
	ds_read_b128 v[212:215], v149 offset:5120
	ds_read_b128 v[216:219], v149 offset:6144
	ds_read_b128 v[228:231], v149 offset:7168
	buffer_load_dwordx4 v144, s[8:11], s56 offen lds
	s_mov_b32 m0, s46
	s_nop 0
	buffer_load_dwordx4 v146, s[8:11], s56 offen lds
	s_waitcnt vmcnt(4)
	s_waitcnt lgkmcnt(0)
	s_setprio 1
	s_barrier
	v_mfma_f32_16x16x32_bf16 v[120:123], v[132:135], v[172:175], v[120:123]
	v_mfma_f32_16x16x32_bf16 v[112:115], v[140:143], v[172:175], v[112:115]
	v_mfma_f32_16x16x32_bf16 v[100:103], v[132:135], v[180:183], v[100:103]
	v_mfma_f32_16x16x32_bf16 v[88:91], v[140:143], v[180:183], v[88:91]
	v_mfma_f32_16x16x32_bf16 v[68:71], v[132:135], v[188:191], v[68:71]
	v_mfma_f32_16x16x32_bf16 v[56:59], v[140:143], v[188:191], v[56:59]
	v_mfma_f32_16x16x32_bf16 v[36:39], v[132:135], v[216:219], v[36:39]
	v_mfma_f32_16x16x32_bf16 v[28:31], v[140:143], v[216:219], v[28:31]
	v_mfma_f32_16x16x32_bf16 v[120:123], v[136:139], v[176:179], v[120:123]
	v_mfma_f32_16x16x32_bf16 v[112:115], v[152:155], v[176:179], v[112:115]
	v_mfma_f32_16x16x32_bf16 v[100:103], v[136:139], v[184:187], v[100:103]
	v_mfma_f32_16x16x32_bf16 v[88:91], v[152:155], v[184:187], v[88:91]
	v_mfma_f32_16x16x32_bf16 v[68:71], v[136:139], v[212:215], v[68:71]
	v_mfma_f32_16x16x32_bf16 v[56:59], v[152:155], v[212:215], v[56:59]
	v_mfma_f32_16x16x32_bf16 v[36:39], v[136:139], v[228:231], v[36:39]
	v_mfma_f32_16x16x32_bf16 v[28:31], v[152:155], v[228:231], v[28:31]
	v_mfma_f32_16x16x32_bf16 v[128:131], v[156:159], v[172:175], v[128:131]
	v_mfma_f32_16x16x32_bf16 v[124:127], v[164:167], v[172:175], v[124:127]
	v_mfma_f32_16x16x32_bf16 v[116:119], v[156:159], v[180:183], v[116:119]
	v_mfma_f32_16x16x32_bf16 v[108:111], v[164:167], v[180:183], v[108:111]
	v_mfma_f32_16x16x32_bf16 v[92:95], v[156:159], v[188:191], v[92:95]
	v_mfma_f32_16x16x32_bf16 v[80:83], v[164:167], v[188:191], v[80:83]
	v_mfma_f32_16x16x32_bf16 v[64:67], v[156:159], v[216:219], v[64:67]
	v_mfma_f32_16x16x32_bf16 v[48:51], v[164:167], v[216:219], v[48:51]
	v_mfma_f32_16x16x32_bf16 v[128:131], v[160:163], v[176:179], v[128:131]
	v_mfma_f32_16x16x32_bf16 v[124:127], v[168:171], v[176:179], v[124:127]
	v_mfma_f32_16x16x32_bf16 v[116:119], v[160:163], v[184:187], v[116:119]
	v_mfma_f32_16x16x32_bf16 v[108:111], v[168:171], v[184:187], v[108:111]
	v_mfma_f32_16x16x32_bf16 v[92:95], v[160:163], v[212:215], v[92:95]
	v_mfma_f32_16x16x32_bf16 v[80:83], v[168:171], v[212:215], v[80:83]
	v_mfma_f32_16x16x32_bf16 v[64:67], v[160:163], v[228:231], v[64:67]
	v_mfma_f32_16x16x32_bf16 v[48:51], v[168:171], v[228:231], v[48:51]
	s_barrier
	s_setprio 0
	s_add_i32 s12, s56, 0xfffc0080
	s_cmp_eq_u32 s29, 12
	s_cselect_b32 s60, s68, s12
	s_cselect_b32 s13, s5, s77
	s_cselect_b32 s12, s4, s76
	s_cselect_b32 s15, s7, s55
	s_cselect_b32 s14, s6, s54
	s_cselect_b32 s58, s69, s57
	s_cselect_b32 s16, s0, s8
	s_cselect_b32 s17, s1, s9
	s_cselect_b32 s18, s2, s10
	s_cselect_b32 s19, s3, s11
	s_or_b32 s59, s60, 0x80
	s_mov_b32 m0, s92
	ds_read_b128 v[172:175], v149 offset:16384
	ds_read_b128 v[176:179], v149 offset:17408
	ds_read_b128 v[180:183], v149 offset:18432
	ds_read_b128 v[184:187], v149 offset:19456
	ds_read_b128 v[188:191], v149 offset:20480
	ds_read_b128 v[212:215], v149 offset:21504
	ds_read_b128 v[216:219], v149 offset:22528
	ds_read_b128 v[228:231], v149 offset:23552
	v_add_u32_e32 v199, 0x1c000, v148
	ds_read_b128 v[194:197], v199
	ds_read_b128 v[200:203], v199 offset:1024
	ds_read_b128 v[206:209], v199 offset:2048
	ds_read_b128 v[220:223], v199 offset:3072
	buffer_load_dwordx4 v145, s[12:15], s58 offen lds
	s_mov_b32 m0, s93
	s_add_i32 s61, s58, 0x40000
	buffer_load_dwordx4 v147, s[12:15], s58 offen lds
	s_mov_b32 m0, s94
	s_nop 0
	buffer_load_dwordx4 v145, s[12:15], s61 offen lds
	s_mov_b32 m0, s95
	s_nop 0
	buffer_load_dwordx4 v147, s[12:15], s61 offen lds
	s_waitcnt vmcnt(6)
	s_waitcnt lgkmcnt(0)
	s_setprio 1
	s_barrier
	v_mfma_f32_16x16x32_bf16 v[72:75], v[132:135], v[172:175], v[72:75]
	v_mfma_f32_16x16x32_bf16 v[60:63], v[140:143], v[172:175], v[60:63]
	v_mfma_f32_16x16x32_bf16 v[40:43], v[132:135], v[180:183], v[40:43]
	v_mfma_f32_16x16x32_bf16 v[32:35], v[140:143], v[180:183], v[32:35]
	v_mfma_f32_16x16x32_bf16 v[16:19], v[132:135], v[188:191], v[16:19]
	v_mfma_f32_16x16x32_bf16 v[12:15], v[140:143], v[188:191], v[12:15]
	v_mfma_f32_16x16x32_bf16 v[8:11], v[132:135], v[216:219], v[8:11]
	v_mfma_f32_16x16x32_bf16 v[2:5], v[140:143], v[216:219], v[4:7]
	v_mfma_f32_16x16x32_bf16 v[72:75], v[136:139], v[176:179], v[72:75]
	v_mfma_f32_16x16x32_bf16 v[60:63], v[152:155], v[176:179], v[60:63]
	v_mfma_f32_16x16x32_bf16 v[40:43], v[136:139], v[184:187], v[40:43]
	v_mfma_f32_16x16x32_bf16 v[32:35], v[152:155], v[184:187], v[32:35]
	v_mfma_f32_16x16x32_bf16 v[16:19], v[136:139], v[212:215], v[16:19]
	v_mfma_f32_16x16x32_bf16 v[12:15], v[152:155], v[212:215], v[12:15]
	v_mfma_f32_16x16x32_bf16 v[8:11], v[136:139], v[228:231], v[8:11]
	v_mfma_f32_16x16x32_bf16 v[2:5], v[152:155], v[228:231], v[2:5]
	v_mfma_f32_16x16x32_bf16 v[96:99], v[156:159], v[172:175], v[96:99]
	v_mfma_f32_16x16x32_bf16 v[104:107], v[164:167], v[172:175], v[104:107]
	v_mfma_f32_16x16x32_bf16 v[84:87], v[156:159], v[180:183], v[84:87]
	v_mfma_f32_16x16x32_bf16 v[76:79], v[164:167], v[180:183], v[76:79]
	v_mfma_f32_16x16x32_bf16 v[52:55], v[156:159], v[188:191], v[52:55]
	v_mfma_f32_16x16x32_bf16 v[44:47], v[164:167], v[188:191], v[44:47]
	v_mfma_f32_16x16x32_bf16 v[24:27], v[156:159], v[216:219], v[24:27]
	v_mfma_f32_16x16x32_bf16 v[20:23], v[164:167], v[216:219], v[20:23]
	v_mfma_f32_16x16x32_bf16 v[96:99], v[160:163], v[176:179], v[96:99]
	v_mfma_f32_16x16x32_bf16 v[104:107], v[168:171], v[176:179], v[104:107]
	v_mfma_f32_16x16x32_bf16 v[84:87], v[160:163], v[184:187], v[84:87]
	v_mfma_f32_16x16x32_bf16 v[76:79], v[168:171], v[184:187], v[76:79]
	v_mfma_f32_16x16x32_bf16 v[52:55], v[160:163], v[212:215], v[52:55]
	v_mfma_f32_16x16x32_bf16 v[44:47], v[168:171], v[212:215], v[44:47]
	v_mfma_f32_16x16x32_bf16 v[24:27], v[160:163], v[228:231], v[24:27]
	v_mfma_f32_16x16x32_bf16 v[20:23], v[168:171], v[228:231], v[20:23]
	s_barrier
	s_setprio 0
	s_mov_b32 m0, s44
	s_nop 0
	buffer_load_dwordx4 v144, s[16:19], s60 offen lds
	s_mov_b32 m0, s36
	s_nop 0
	buffer_load_dwordx4 v146, s[16:19], s60 offen lds
	v_add_u32_e32 v152, 0x18000, v148
	v_add_u32_e32 v153, 0x1c000, v148
	ds_read_b128 v[132:135], v152
	ds_read_b128 v[136:139], v152 offset:1024
	ds_read_b128 v[140:143], v152 offset:2048
	ds_read_b128 v[154:157], v152 offset:3072
	s_add_i32 s60, s60, 0x40000
	s_mov_b32 m0, s37
	ds_read_b128 v[174:177], v149 offset:32768
	ds_read_b128 v[178:181], v149 offset:33792
	ds_read_b128 v[182:185], v149 offset:34816
	ds_read_b128 v[186:189], v149 offset:35840
	ds_read_b128 v[190:193], v149 offset:36864
	ds_read_b128 v[212:215], v149 offset:37888
	ds_read_b128 v[216:219], v149 offset:38912
	ds_read_b128 v[228:231], v149 offset:39936
	buffer_load_dwordx4 v144, s[16:19], s60 offen lds
	s_mov_b32 m0, s38
	s_nop 0
	buffer_load_dwordx4 v146, s[16:19], s60 offen lds
	s_waitcnt vmcnt(8)
	s_waitcnt lgkmcnt(0)
	s_setprio 1
	s_barrier
	v_mfma_f32_16x16x32_bf16 v[120:123], v[132:135], v[174:177], v[120:123]
	v_mfma_f32_16x16x32_bf16 v[112:115], v[140:143], v[174:177], v[112:115]
	v_mfma_f32_16x16x32_bf16 v[100:103], v[132:135], v[182:185], v[100:103]
	v_mfma_f32_16x16x32_bf16 v[88:91], v[140:143], v[182:185], v[88:91]
	v_mfma_f32_16x16x32_bf16 v[68:71], v[132:135], v[190:193], v[68:71]
	v_mfma_f32_16x16x32_bf16 v[56:59], v[140:143], v[190:193], v[56:59]
	v_mfma_f32_16x16x32_bf16 v[36:39], v[132:135], v[216:219], v[36:39]
	v_mfma_f32_16x16x32_bf16 v[28:31], v[140:143], v[216:219], v[28:31]
	v_mfma_f32_16x16x32_bf16 v[120:123], v[136:139], v[178:181], v[120:123]
	v_mfma_f32_16x16x32_bf16 v[112:115], v[154:157], v[178:181], v[112:115]
	v_mfma_f32_16x16x32_bf16 v[100:103], v[136:139], v[186:189], v[100:103]
	v_mfma_f32_16x16x32_bf16 v[88:91], v[154:157], v[186:189], v[88:91]
	v_mfma_f32_16x16x32_bf16 v[68:71], v[136:139], v[212:215], v[68:71]
	v_mfma_f32_16x16x32_bf16 v[56:59], v[154:157], v[212:215], v[56:59]
	v_mfma_f32_16x16x32_bf16 v[36:39], v[136:139], v[228:231], v[36:39]
	v_mfma_f32_16x16x32_bf16 v[28:31], v[154:157], v[228:231], v[28:31]
	v_mfma_f32_16x16x32_bf16 v[128:131], v[194:197], v[174:177], v[128:131]
	v_mfma_f32_16x16x32_bf16 v[124:127], v[206:209], v[174:177], v[124:127]
	v_mfma_f32_16x16x32_bf16 v[116:119], v[194:197], v[182:185], v[116:119]
	v_mfma_f32_16x16x32_bf16 v[108:111], v[206:209], v[182:185], v[108:111]
	v_mfma_f32_16x16x32_bf16 v[92:95], v[194:197], v[190:193], v[92:95]
	v_mfma_f32_16x16x32_bf16 v[80:83], v[206:209], v[190:193], v[80:83]
	v_mfma_f32_16x16x32_bf16 v[64:67], v[194:197], v[216:219], v[64:67]
	v_mfma_f32_16x16x32_bf16 v[48:51], v[206:209], v[216:219], v[48:51]
	v_mfma_f32_16x16x32_bf16 v[128:131], v[200:203], v[178:181], v[128:131]
	v_mfma_f32_16x16x32_bf16 v[124:127], v[220:223], v[178:181], v[124:127]
	v_mfma_f32_16x16x32_bf16 v[116:119], v[200:203], v[186:189], v[116:119]
	v_mfma_f32_16x16x32_bf16 v[108:111], v[220:223], v[186:189], v[108:111]
	v_mfma_f32_16x16x32_bf16 v[92:95], v[200:203], v[212:215], v[92:95]
	v_mfma_f32_16x16x32_bf16 v[80:83], v[220:223], v[212:215], v[80:83]
	v_mfma_f32_16x16x32_bf16 v[64:67], v[200:203], v[228:231], v[64:67]
	v_mfma_f32_16x16x32_bf16 v[48:51], v[220:223], v[228:231], v[48:51]
	s_barrier
; #define PG8_STAGE(bufoff, gbase, voff) do { const Src _g = (gbase); _Pragma("unroll") for (int _i = 0; _i < 2; ++_i) \
;         __builtin_amdgcn_raw_ptr_buffer_load_lds(_g.r, (LAS unsigned*)(lds + (bufoff) + ldsw + _i * 8192), 16, (voff)[_i], _g.o, 0, 0); } while (0)
; #define PG8_WAIT_V(n) asm volatile("s_waitcnt vmcnt(" #n ")" ::: "memory")
; template <class Epi, bool ALIGN_EPI, bool SP2, class Hook>
; __device__ __forceinline__ void gemm_phase(LAS unsigned char* lds, const Gemm g, const StaticOrder& S, const Epi& E, Acc& acc, const bool fresh, const Hook& H, const int wave_id) {
;     ...
;         for (int t = t0; t < nt; t += 2) {
;             const bool last = (t == nt - 2);
;             const Src a1 = cA + (size_t)(t + 1) * kstep;
;             const Src a2 = last ? nA : cA + (size_t)(t + 2) * kstep, b2 = last ? nB : cB + (size_t)(t + 2) * kstep;
;             const Src a3 = a2 + kstep, b3 = b2 + kstep;
;             if (last && has_next) H(nxt);
;             if constexpr (SP2) {
;             PG8_TRIP_SP2(PG8_WAIT_V(8));
;             } else {
;             PG8_LDB(B0, 0, 0); PG8_SCHED; PG8_LDA(At, 0, 0); PG8_STAGE(PG8_SA(1, 1), a1 + hstepA, voffA);
;             PG8_WAIT_L(8); PG8_BAR; PG8_WAIT_L(0); PG8_MMA(0, 0, At, B0); PG8_BAR; PG8_SCHED;
;             PG8_LDB(B1, 0, 1); PG8_STAGE(PG8_SB(0, 0), b2, voffB);
;             PG8_BAR; PG8_WAIT_L(0); PG8_MMA(0, 1, At, B1); PG8_BAR;
;             PG8_LDA(At, 0, 1); PG8_STAGE(PG8_SA(0, 0), a2, voffA);
;             PG8_BAR; PG8_WAIT_L(0); PG8_MMA(1, 0, At, B0); PG8_BAR; PG8_SCHED;
;             PG8_STAGE(PG8_SB(0, 1), b2 + hstep, voffB);
;             PG8_WAIT_V(6); PG8_BAR; PG8_MMA(1, 1, At, B1); PG8_BAR;
;             PG8_LDB(B0, 1, 0); PG8_SCHED; PG8_LDA(At, 1, 0); PG8_STAGE(PG8_SA(0, 1), a2 + hstepA, voffA);
;             PG8_WAIT_L(8); PG8_BAR; PG8_WAIT_L(0); PG8_MMA(0, 0, At, B0); PG8_BAR; PG8_SCHED;
;             PG8_LDB(B1, 1, 1); PG8_STAGE(PG8_SB(1, 0), b3, voffB);
;             PG8_BAR; PG8_WAIT_L(0); PG8_MMA(0, 1, At, B1); PG8_BAR;
;             PG8_LDA(At, 1, 1); PG8_STAGE(PG8_SA(1, 0), a3, voffA);
;             PG8_BAR; PG8_WAIT_L(0); PG8_MMA(1, 0, At, B0); PG8_BAR; PG8_SCHED;
;             PG8_STAGE(PG8_SB(1, 1), b3 + hstep, voffB);
;             PG8_WAIT_V(6); PG8_BAR; PG8_MMA(1, 1, At, B1); PG8_BAR;
;             }
;         }
;         if constexpr (ALIGN_EPI) { if (wr == 0) PG8_BAR; }
	s_setprio 0
	s_mov_b32 m0, s39
	s_or_b32 s60, s58, 0x80
	ds_read_b128 v[174:177], v149 offset:49152
	ds_read_b128 v[178:181], v149 offset:50176
	ds_read_b128 v[182:185], v149 offset:51200
	ds_read_b128 v[186:189], v149 offset:52224
	ds_read_b128 v[190:193], v149 offset:53248
	ds_read_b128 v[212:215], v149 offset:54272
	ds_read_b128 v[216:219], v149 offset:55296
	ds_read_b128 v[228:231], v149 offset:56320
	buffer_load_dwordx4 v145, s[12:15], s60 offen lds
	s_mov_b32 m0, s40
	s_add_i32 s58, s58, 0x40080
	buffer_load_dwordx4 v147, s[12:15], s60 offen lds
	s_mov_b32 m0, s43
	s_nop 0
	buffer_load_dwordx4 v145, s[12:15], s58 offen lds
	s_mov_b32 m0, s42
	s_nop 0
	buffer_load_dwordx4 v147, s[12:15], s58 offen lds
	s_waitcnt vmcnt(6)
	s_waitcnt lgkmcnt(0)
	s_setprio 1
	s_barrier
	v_mfma_f32_16x16x32_bf16 v[72:75], v[132:135], v[174:177], v[72:75]
	v_mfma_f32_16x16x32_bf16 v[60:63], v[140:143], v[174:177], v[60:63]
	v_mfma_f32_16x16x32_bf16 v[40:43], v[132:135], v[182:185], v[40:43]
	v_mfma_f32_16x16x32_bf16 v[32:35], v[140:143], v[182:185], v[32:35]
	v_mfma_f32_16x16x32_bf16 v[16:19], v[132:135], v[190:193], v[16:19]
	v_mfma_f32_16x16x32_bf16 v[12:15], v[140:143], v[190:193], v[12:15]
	v_mfma_f32_16x16x32_bf16 v[6:9], v[132:135], v[216:219], v[8:11]
	v_mfma_f32_16x16x32_bf16 v[2:5], v[140:143], v[216:219], v[2:5]
	v_mfma_f32_16x16x32_bf16 v[72:75], v[136:139], v[178:181], v[72:75]
	v_mfma_f32_16x16x32_bf16 v[60:63], v[154:157], v[178:181], v[60:63]
	v_mfma_f32_16x16x32_bf16 v[40:43], v[136:139], v[186:189], v[40:43]
	v_mfma_f32_16x16x32_bf16 v[32:35], v[154:157], v[186:189], v[32:35]
	v_mfma_f32_16x16x32_bf16 v[16:19], v[136:139], v[212:215], v[16:19]
	v_mfma_f32_16x16x32_bf16 v[12:15], v[154:157], v[212:215], v[12:15]
	v_mfma_f32_16x16x32_bf16 v[8:11], v[136:139], v[228:231], v[6:9]
	v_mfma_f32_16x16x32_bf16 v[4:7], v[154:157], v[228:231], v[2:5]
	v_mfma_f32_16x16x32_bf16 v[96:99], v[194:197], v[174:177], v[96:99]
	v_mfma_f32_16x16x32_bf16 v[104:107], v[206:209], v[174:177], v[104:107]
	v_mfma_f32_16x16x32_bf16 v[84:87], v[194:197], v[182:185], v[84:87]
	v_mfma_f32_16x16x32_bf16 v[76:79], v[206:209], v[182:185], v[76:79]
	v_mfma_f32_16x16x32_bf16 v[52:55], v[194:197], v[190:193], v[52:55]
	v_mfma_f32_16x16x32_bf16 v[44:47], v[206:209], v[190:193], v[44:47]
	v_mfma_f32_16x16x32_bf16 v[24:27], v[194:197], v[216:219], v[24:27]
	v_mfma_f32_16x16x32_bf16 v[20:23], v[206:209], v[216:219], v[20:23]
	v_mfma_f32_16x16x32_bf16 v[96:99], v[200:203], v[178:181], v[96:99]
	v_mfma_f32_16x16x32_bf16 v[104:107], v[220:223], v[178:181], v[104:107]
	v_mfma_f32_16x16x32_bf16 v[84:87], v[200:203], v[186:189], v[84:87]
	v_mfma_f32_16x16x32_bf16 v[76:79], v[220:223], v[186:189], v[76:79]
	v_mfma_f32_16x16x32_bf16 v[52:55], v[200:203], v[212:215], v[52:55]
	v_mfma_f32_16x16x32_bf16 v[44:47], v[220:223], v[212:215], v[44:47]
	v_mfma_f32_16x16x32_bf16 v[24:27], v[200:203], v[228:231], v[24:27]
	v_mfma_f32_16x16x32_bf16 v[20:23], v[220:223], v[228:231], v[20:23]
	s_barrier
	s_setprio 0
	s_add_i32 s29, s29, 2
	s_addk_i32 s56, 0x100
	s_addk_i32 s57, 0x100
	s_cmp_gt_u32 s29, 13
	s_cbranch_scc0 .LBB0_391
	s_mov_b32 m0, s41
	s_nop 0
	buffer_load_dwordx4 v144, s[16:19], s59 offen lds
	s_mov_b32 m0, s33
	s_nop 0
	buffer_load_dwordx4 v146, s[16:19], s59 offen lds
	v_readlane_b32 s8, v251, 45
	v_readlane_b32 s9, v251, 46
	s_and_b64 vcc, exec, s[8:9]
	s_cbranch_vccz .LBB0_394
	s_barrier

; #define PG8_WAIT_V(n) asm volatile("s_waitcnt vmcnt(" #n ")" ::: "memory")
; template <class Epi, bool ALIGN_EPI, bool SP2, class Hook>
; __device__ __forceinline__ void gemm_phase(LAS unsigned char* lds, const Gemm g, const StaticOrder& S, const Epi& E, Acc& acc, const bool fresh, const Hook& H, const int wave_id) {
;     ...
;         for (int t = t0; t < nt; t += 2) {
;             const bool last = (t == nt - 2);
;             const Src a1 = cA + (size_t)(t + 1) * kstep;
;             const Src a2 = last ? nA : cA + (size_t)(t + 2) * kstep, b2 = last ? nB : cB + (size_t)(t + 2) * kstep;
;             const Src a3 = a2 + kstep, b3 = b2 + kstep;
;             if (last && has_next) H(nxt);
;             if constexpr (SP2) {
;             PG8_TRIP_SP2(PG8_WAIT_V(8));
.LBB0_903:
	s_add_i32 s100, s55, 0xfffe0000
	v_add_u32_e32 v70, 0x10000, v216
	v_add_u32_e32 v118, 0x14000, v216
	ds_read_b128 v[34:37], v70
	ds_read_b128 v[46:49], v70 offset:1024
	ds_read_b128 v[58:61], v70 offset:2048
	ds_read_b128 v[70:73], v70 offset:3072
	ds_read_b128 v[82:85], v118
	ds_read_b128 v[94:97], v118 offset:1024
	ds_read_b128 v[106:109], v118 offset:2048
	ds_read_b128 v[118:121], v118 offset:3072
	s_mov_b32 m0, s41
	s_nop 0
	buffer_load_dwordx4 v0, s[8:11], s100 offen lds
	s_mov_b32 m0, s33
	s_nop 0
	buffer_load_dwordx4 v214, s[8:11], s100 offen lds
	s_mov_b32 m0, s45
	ds_read_b128 v[130:133], v217
	ds_read_b128 v[142:145], v217 offset:1024
	ds_read_b128 v[154:157], v217 offset:2048
	ds_read_b128 v[166:169], v217 offset:3072
	ds_read_b128 v[174:177], v217 offset:4096
	ds_read_b128 v[182:185], v217 offset:5120
	ds_read_b128 v[186:189], v217 offset:6144
	ds_read_b128 v[190:193], v217 offset:7168
	buffer_load_dwordx4 v0, s[8:11], s55 offen lds
	s_mov_b32 m0, s46
	s_nop 0
	buffer_load_dwordx4 v214, s[8:11], s55 offen lds
	s_waitcnt vmcnt(4)
	s_waitcnt lgkmcnt(0)
	s_setprio 1
	s_barrier
	v_mfma_f32_16x16x32_bf16 v[178:181], v[34:37], v[130:133], v[178:181]
	v_mfma_f32_16x16x32_bf16 v[170:173], v[58:61], v[130:133], v[170:173]
	v_mfma_f32_16x16x32_bf16 v[150:153], v[34:37], v[154:157], v[150:153]
	v_mfma_f32_16x16x32_bf16 v[146:149], v[58:61], v[154:157], v[146:149]
	v_mfma_f32_16x16x32_bf16 v[126:129], v[34:37], v[174:177], v[126:129]
	v_mfma_f32_16x16x32_bf16 v[122:125], v[58:61], v[174:177], v[122:125]
	v_mfma_f32_16x16x32_bf16 v[102:105], v[34:37], v[186:189], v[102:105]
	v_mfma_f32_16x16x32_bf16 v[98:101], v[58:61], v[186:189], v[98:101]
	v_mfma_f32_16x16x32_bf16 v[178:181], v[46:49], v[142:145], v[178:181]
	v_mfma_f32_16x16x32_bf16 v[170:173], v[70:73], v[142:145], v[170:173]
	v_mfma_f32_16x16x32_bf16 v[150:153], v[46:49], v[166:169], v[150:153]
	v_mfma_f32_16x16x32_bf16 v[146:149], v[70:73], v[166:169], v[146:149]
	v_mfma_f32_16x16x32_bf16 v[126:129], v[46:49], v[182:185], v[126:129]
	v_mfma_f32_16x16x32_bf16 v[122:125], v[70:73], v[182:185], v[122:125]
	v_mfma_f32_16x16x32_bf16 v[102:105], v[46:49], v[190:193], v[102:105]
	v_mfma_f32_16x16x32_bf16 v[98:101], v[70:73], v[190:193], v[98:101]
	v_mfma_f32_16x16x32_bf16 v[162:165], v[82:85], v[130:133], v[162:165]
	v_mfma_f32_16x16x32_bf16 v[138:141], v[82:85], v[154:157], v[138:141]
	v_mfma_f32_16x16x32_bf16 v[134:137], v[106:109], v[154:157], v[134:137]
	v_mfma_f32_16x16x32_bf16 v[114:117], v[82:85], v[174:177], v[114:117]
	v_mfma_f32_16x16x32_bf16 v[110:113], v[106:109], v[174:177], v[110:113]
	v_mfma_f32_16x16x32_bf16 v[90:93], v[82:85], v[186:189], v[90:93]
	v_mfma_f32_16x16x32_bf16 v[86:89], v[106:109], v[186:189], v[86:89]
	v_mfma_f32_16x16x32_bf16 v[162:165], v[94:97], v[142:145], v[162:165]
	v_mfma_f32_16x16x32_bf16 v[130:133], v[106:109], v[130:133], v[158:161]
	v_mfma_f32_16x16x32_bf16 v[138:141], v[94:97], v[166:169], v[138:141]
	v_mfma_f32_16x16x32_bf16 v[134:137], v[118:121], v[166:169], v[134:137]
	v_mfma_f32_16x16x32_bf16 v[114:117], v[94:97], v[182:185], v[114:117]
	v_mfma_f32_16x16x32_bf16 v[110:113], v[118:121], v[182:185], v[110:113]
	v_mfma_f32_16x16x32_bf16 v[90:93], v[94:97], v[190:193], v[90:93]
	v_mfma_f32_16x16x32_bf16 v[86:89], v[118:121], v[190:193], v[86:89]
	v_mfma_f32_16x16x32_bf16 v[130:133], v[118:121], v[142:145], v[130:133]
	s_barrier
	s_setprio 0
	s_add_i32 s12, s55, 0xfffe0080
	s_cmp_eq_u32 s57, 4
	s_cselect_b32 s60, s53, s12
	s_cselect_b32 s13, s29, s77
	s_cselect_b32 s12, s28, s76
	s_cselect_b32 s15, s31, s35
	s_cselect_b32 s14, s30, s34
	s_cselect_b32 s58, s54, s56
	s_cselect_b32 s16, s2, s8
	s_cselect_b32 s17, s3, s9
	s_cselect_b32 s18, s26, s10
	s_cselect_b32 s19, s27, s11
	s_or_b32 s59, s60, 0x80
	s_mov_b32 m0, s92
	ds_read_b128 v[142:145], v217 offset:16384
	ds_read_b128 v[154:157], v217 offset:17408
	ds_read_b128 v[158:161], v217 offset:18432
	ds_read_b128 v[166:169], v217 offset:19456
	ds_read_b128 v[174:177], v217 offset:20480
	ds_read_b128 v[182:185], v217 offset:21504
	ds_read_b128 v[186:189], v217 offset:22528
	ds_read_b128 v[190:193], v217 offset:23552
	v_add_u32_e32 v204, 0x1c000, v216
	ds_read_b128 v[200:203], v204
	ds_read_b128 v[206:209], v204 offset:1024
	ds_read_b128 v[210:213], v204 offset:2048
	ds_read_b128 v[218:221], v204 offset:3072
	buffer_load_dwordx4 v199, s[12:15], s58 offen lds
	s_mov_b32 m0, s93
	s_add_i32 s61, s58, 0x20000
	buffer_load_dwordx4 v215, s[12:15], s58 offen lds
	s_mov_b32 m0, s94
	s_nop 0
	buffer_load_dwordx4 v199, s[12:15], s61 offen lds
	s_mov_b32 m0, s95
	s_nop 0
	buffer_load_dwordx4 v215, s[12:15], s61 offen lds
	s_waitcnt vmcnt(6)
	s_waitcnt lgkmcnt(0)
	s_setprio 1
	s_barrier
	v_mfma_f32_16x16x32_bf16 v[78:81], v[34:37], v[142:145], v[78:81]
	v_mfma_f32_16x16x32_bf16 v[74:77], v[58:61], v[142:145], v[74:77]
	v_mfma_f32_16x16x32_bf16 v[54:57], v[34:37], v[158:161], v[54:57]
	v_mfma_f32_16x16x32_bf16 v[50:53], v[58:61], v[158:161], v[50:53]
	v_mfma_f32_16x16x32_bf16 v[30:33], v[34:37], v[174:177], v[30:33]
	v_mfma_f32_16x16x32_bf16 v[26:29], v[58:61], v[174:177], v[26:29]
	v_mfma_f32_16x16x32_bf16 v[14:17], v[34:37], v[186:189], v[14:17]
	v_mfma_f32_16x16x32_bf16 v[10:13], v[58:61], v[186:189], v[10:13]
	v_mfma_f32_16x16x32_bf16 v[78:81], v[46:49], v[154:157], v[78:81]
	v_mfma_f32_16x16x32_bf16 v[74:77], v[70:73], v[154:157], v[74:77]
	v_mfma_f32_16x16x32_bf16 v[54:57], v[46:49], v[166:169], v[54:57]
	v_mfma_f32_16x16x32_bf16 v[50:53], v[70:73], v[166:169], v[50:53]
	v_mfma_f32_16x16x32_bf16 v[30:33], v[46:49], v[182:185], v[30:33]
	v_mfma_f32_16x16x32_bf16 v[26:29], v[70:73], v[182:185], v[26:29]
	v_mfma_f32_16x16x32_bf16 v[14:17], v[46:49], v[190:193], v[14:17]
	v_mfma_f32_16x16x32_bf16 v[10:13], v[70:73], v[190:193], v[10:13]
	v_mfma_f32_16x16x32_bf16 v[42:45], v[82:85], v[158:161], v[42:45]
	v_mfma_f32_16x16x32_bf16 v[38:41], v[106:109], v[158:161], v[38:41]
	v_mfma_f32_16x16x32_bf16 v[22:25], v[82:85], v[174:177], v[22:25]
	v_mfma_f32_16x16x32_bf16 v[18:21], v[106:109], v[174:177], v[18:21]
	v_mfma_f32_16x16x32_bf16 v[6:9], v[82:85], v[186:189], v[6:9]
	v_mfma_f32_16x16x32_bf16 v[2:5], v[106:109], v[186:189], v[2:5]
	v_mfma_f32_16x16x32_bf16 v[34:37], v[82:85], v[142:145], v[66:69]
	v_mfma_f32_16x16x32_bf16 v[46:49], v[106:109], v[142:145], v[62:65]
	v_mfma_f32_16x16x32_bf16 v[42:45], v[94:97], v[166:169], v[42:45]
	v_mfma_f32_16x16x32_bf16 v[38:41], v[118:121], v[166:169], v[38:41]
	v_mfma_f32_16x16x32_bf16 v[22:25], v[94:97], v[182:185], v[22:25]
	v_mfma_f32_16x16x32_bf16 v[18:21], v[118:121], v[182:185], v[18:21]
	v_mfma_f32_16x16x32_bf16 v[6:9], v[94:97], v[190:193], v[6:9]
	v_mfma_f32_16x16x32_bf16 v[2:5], v[118:121], v[190:193], v[2:5]
	v_mfma_f32_16x16x32_bf16 v[34:37], v[94:97], v[154:157], v[34:37]
	v_mfma_f32_16x16x32_bf16 v[46:49], v[118:121], v[154:157], v[46:49]
	s_barrier
	s_setprio 0
	s_mov_b32 m0, s44
	s_nop 0
	buffer_load_dwordx4 v0, s[16:19], s60 offen lds
	s_mov_b32 m0, s36
	s_nop 0
	buffer_load_dwordx4 v214, s[16:19], s60 offen lds
	v_add_u32_e32 v70, 0x18000, v216
	v_add_u32_e32 v118, 0x1c000, v216
	ds_read_b128 v[58:61], v70
	ds_read_b128 v[62:65], v70 offset:1024
	ds_read_b128 v[66:69], v70 offset:2048
	ds_read_b128 v[70:73], v70 offset:3072
	s_add_i32 s60, s60, 0x20000
	s_mov_b32 m0, s37
	ds_read_b128 v[142:145], v217 offset:32768
	ds_read_b128 v[154:157], v217 offset:33792
	ds_read_b128 v[166:169], v217 offset:34816
	ds_read_b128 v[174:177], v217 offset:35840
	ds_read_b128 v[182:185], v217 offset:36864
	ds_read_b128 v[186:189], v217 offset:37888
	ds_read_b128 v[190:193], v217 offset:38912
	ds_read_b128 v[194:197], v217 offset:39936
	buffer_load_dwordx4 v0, s[16:19], s60 offen lds
	s_mov_b32 m0, s38
	s_nop 0
	buffer_load_dwordx4 v214, s[16:19], s60 offen lds
	s_waitcnt vmcnt(8)
	s_waitcnt lgkmcnt(0)
	s_setprio 1
	s_barrier
	v_mfma_f32_16x16x32_bf16 v[158:161], v[58:61], v[142:145], v[178:181]
	v_mfma_f32_16x16x32_bf16 v[178:181], v[62:65], v[154:157], v[158:161]
	v_mfma_f32_16x16x32_bf16 v[158:161], v[66:69], v[142:145], v[170:173]
	v_mfma_f32_16x16x32_bf16 v[150:153], v[58:61], v[166:169], v[150:153]
	v_mfma_f32_16x16x32_bf16 v[146:149], v[66:69], v[166:169], v[146:149]
	v_mfma_f32_16x16x32_bf16 v[126:129], v[58:61], v[182:185], v[126:129]
	v_mfma_f32_16x16x32_bf16 v[122:125], v[66:69], v[182:185], v[122:125]
	v_mfma_f32_16x16x32_bf16 v[102:105], v[58:61], v[190:193], v[102:105]
	v_mfma_f32_16x16x32_bf16 v[98:101], v[66:69], v[190:193], v[98:101]
	v_mfma_f32_16x16x32_bf16 v[170:173], v[70:73], v[154:157], v[158:161]
	v_mfma_f32_16x16x32_bf16 v[150:153], v[62:65], v[174:177], v[150:153]
	v_mfma_f32_16x16x32_bf16 v[146:149], v[70:73], v[174:177], v[146:149]
	v_mfma_f32_16x16x32_bf16 v[126:129], v[62:65], v[186:189], v[126:129]
	v_mfma_f32_16x16x32_bf16 v[122:125], v[70:73], v[186:189], v[122:125]
	v_mfma_f32_16x16x32_bf16 v[102:105], v[62:65], v[194:197], v[102:105]
	v_mfma_f32_16x16x32_bf16 v[98:101], v[70:73], v[194:197], v[98:101]
	v_mfma_f32_16x16x32_bf16 v[158:161], v[200:203], v[142:145], v[162:165]
	v_mfma_f32_16x16x32_bf16 v[130:133], v[210:213], v[142:145], v[130:133]
	v_mfma_f32_16x16x32_bf16 v[162:165], v[206:209], v[154:157], v[158:161]
	v_mfma_f32_16x16x32_bf16 v[158:161], v[218:221], v[154:157], v[130:133]
	v_mfma_f32_16x16x32_bf16 v[130:133], v[200:203], v[166:169], v[138:141]
	v_mfma_f32_16x16x32_bf16 v[138:141], v[206:209], v[174:177], v[130:133]
	v_mfma_f32_16x16x32_bf16 v[130:133], v[210:213], v[166:169], v[134:137]
	v_mfma_f32_16x16x32_bf16 v[114:117], v[200:203], v[182:185], v[114:117]
	v_mfma_f32_16x16x32_bf16 v[110:113], v[210:213], v[182:185], v[110:113]
	v_mfma_f32_16x16x32_bf16 v[90:93], v[200:203], v[190:193], v[90:93]
	v_mfma_f32_16x16x32_bf16 v[86:89], v[210:213], v[190:193], v[86:89]
	v_mfma_f32_16x16x32_bf16 v[134:137], v[218:221], v[174:177], v[130:133]
	v_mfma_f32_16x16x32_bf16 v[114:117], v[206:209], v[186:189], v[114:117]
	v_mfma_f32_16x16x32_bf16 v[110:113], v[218:221], v[186:189], v[110:113]
	v_mfma_f32_16x16x32_bf16 v[90:93], v[206:209], v[194:197], v[90:93]
	v_mfma_f32_16x16x32_bf16 v[86:89], v[218:221], v[194:197], v[86:89]
	s_barrier
; #define PG8_STAGE(bufoff, gbase, voff) do { const Src _g = (gbase); _Pragma("unroll") for (int _i = 0; _i < 2; ++_i) \
;         __builtin_amdgcn_raw_ptr_buffer_load_lds(_g.r, (LAS unsigned*)(lds + (bufoff) + ldsw + _i * 8192), 16, (voff)[_i], _g.o, 0, 0); } while (0)
; #define PG8_WAIT_V(n) asm volatile("s_waitcnt vmcnt(" #n ")" ::: "memory")
; template <class Epi, bool ALIGN_EPI, bool SP2, class Hook>
; __device__ __forceinline__ void gemm_phase(LAS unsigned char* lds, const Gemm g, const StaticOrder& S, const Epi& E, Acc& acc, const bool fresh, const Hook& H, const int wave_id) {
;     ...
;         for (int t = t0; t < nt; t += 2) {
;             const bool last = (t == nt - 2);
;             const Src a1 = cA + (size_t)(t + 1) * kstep;
;             const Src a2 = last ? nA : cA + (size_t)(t + 2) * kstep, b2 = last ? nB : cB + (size_t)(t + 2) * kstep;
;             const Src a3 = a2 + kstep, b3 = b2 + kstep;
;             if (last && has_next) H(nxt);
;             if constexpr (SP2) {
;             PG8_TRIP_SP2(PG8_WAIT_V(8));
;             } else {
;             PG8_LDB(B0, 0, 0); PG8_SCHED; PG8_LDA(At, 0, 0); PG8_STAGE(PG8_SA(1, 1), a1 + hstepA, voffA);
;             PG8_WAIT_L(8); PG8_BAR; PG8_WAIT_L(0); PG8_MMA(0, 0, At, B0); PG8_BAR; PG8_SCHED;
;             PG8_LDB(B1, 0, 1); PG8_STAGE(PG8_SB(0, 0), b2, voffB);
;             PG8_BAR; PG8_WAIT_L(0); PG8_MMA(0, 1, At, B1); PG8_BAR;
;             PG8_LDA(At, 0, 1); PG8_STAGE(PG8_SA(0, 0), a2, voffA);
;             PG8_BAR; PG8_WAIT_L(0); PG8_MMA(1, 0, At, B0); PG8_BAR; PG8_SCHED;
;             PG8_STAGE(PG8_SB(0, 1), b2 + hstep, voffB);
;             PG8_WAIT_V(6); PG8_BAR; PG8_MMA(1, 1, At, B1); PG8_BAR;
;             PG8_LDB(B0, 1, 0); PG8_SCHED; PG8_LDA(At, 1, 0); PG8_STAGE(PG8_SA(0, 1), a2 + hstepA, voffA);
;             PG8_WAIT_L(8); PG8_BAR; PG8_WAIT_L(0); PG8_MMA(0, 0, At, B0); PG8_BAR; PG8_SCHED;
;             PG8_LDB(B1, 1, 1); PG8_STAGE(PG8_SB(1, 0), b3, voffB);
;             PG8_BAR; PG8_WAIT_L(0); PG8_MMA(0, 1, At, B1); PG8_BAR;
;             PG8_LDA(At, 1, 1); PG8_STAGE(PG8_SA(1, 0), a3, voffA);
;             PG8_BAR; PG8_WAIT_L(0); PG8_MMA(1, 0, At, B0); PG8_BAR; PG8_SCHED;
;             PG8_STAGE(PG8_SB(1, 1), b3 + hstep, voffB);
;             PG8_WAIT_V(6); PG8_BAR; PG8_MMA(1, 1, At, B1); PG8_BAR;
;             }
;         }
;         if constexpr (ALIGN_EPI) { if (wr == 0) PG8_BAR; }
	s_setprio 0
	s_mov_b32 m0, s39
	s_or_b32 s60, s58, 0x80
	ds_read_b128 v[130:133], v217 offset:49152
	ds_read_b128 v[142:145], v217 offset:50176
	ds_read_b128 v[154:157], v217 offset:51200
	ds_read_b128 v[166:169], v217 offset:52224
	ds_read_b128 v[174:177], v217 offset:53248
	ds_read_b128 v[182:185], v217 offset:54272
	ds_read_b128 v[186:189], v217 offset:55296
	ds_read_b128 v[190:193], v217 offset:56320
	buffer_load_dwordx4 v199, s[12:15], s60 offen lds
	s_mov_b32 m0, s40
	s_add_i32 s58, s58, 0x20080
	buffer_load_dwordx4 v215, s[12:15], s60 offen lds
	s_mov_b32 m0, s43
	s_nop 0
	buffer_load_dwordx4 v199, s[12:15], s58 offen lds
	s_mov_b32 m0, s42
	s_nop 0
	buffer_load_dwordx4 v215, s[12:15], s58 offen lds
	s_waitcnt vmcnt(6)
	s_waitcnt lgkmcnt(0)
	s_setprio 1
	s_barrier
	v_mfma_f32_16x16x32_bf16 v[78:81], v[58:61], v[130:133], v[78:81]
	v_mfma_f32_16x16x32_bf16 v[74:77], v[66:69], v[130:133], v[74:77]
	v_mfma_f32_16x16x32_bf16 v[54:57], v[58:61], v[154:157], v[54:57]
	v_mfma_f32_16x16x32_bf16 v[50:53], v[66:69], v[154:157], v[50:53]
	v_mfma_f32_16x16x32_bf16 v[30:33], v[58:61], v[174:177], v[30:33]
	v_mfma_f32_16x16x32_bf16 v[26:29], v[66:69], v[174:177], v[26:29]
	v_mfma_f32_16x16x32_bf16 v[14:17], v[58:61], v[186:189], v[14:17]
	v_mfma_f32_16x16x32_bf16 v[10:13], v[66:69], v[186:189], v[10:13]
	v_mfma_f32_16x16x32_bf16 v[78:81], v[62:65], v[142:145], v[78:81]
	v_mfma_f32_16x16x32_bf16 v[74:77], v[70:73], v[142:145], v[74:77]
	v_mfma_f32_16x16x32_bf16 v[54:57], v[62:65], v[166:169], v[54:57]
	v_mfma_f32_16x16x32_bf16 v[50:53], v[70:73], v[166:169], v[50:53]
	v_mfma_f32_16x16x32_bf16 v[30:33], v[62:65], v[182:185], v[30:33]
	v_mfma_f32_16x16x32_bf16 v[26:29], v[70:73], v[182:185], v[26:29]
	v_mfma_f32_16x16x32_bf16 v[14:17], v[62:65], v[190:193], v[14:17]
	v_mfma_f32_16x16x32_bf16 v[10:13], v[70:73], v[190:193], v[10:13]
	v_mfma_f32_16x16x32_bf16 v[34:37], v[200:203], v[130:133], v[34:37]
	v_mfma_f32_16x16x32_bf16 v[66:69], v[206:209], v[142:145], v[34:37]
	v_mfma_f32_16x16x32_bf16 v[34:37], v[210:213], v[130:133], v[46:49]
	v_mfma_f32_16x16x32_bf16 v[62:65], v[218:221], v[142:145], v[34:37]
	v_mfma_f32_16x16x32_bf16 v[34:37], v[200:203], v[154:157], v[42:45]
	v_mfma_f32_16x16x32_bf16 v[42:45], v[206:209], v[166:169], v[34:37]
	v_mfma_f32_16x16x32_bf16 v[34:37], v[210:213], v[154:157], v[38:41]
	v_mfma_f32_16x16x32_bf16 v[22:25], v[200:203], v[174:177], v[22:25]
	v_mfma_f32_16x16x32_bf16 v[18:21], v[210:213], v[174:177], v[18:21]
	v_mfma_f32_16x16x32_bf16 v[6:9], v[200:203], v[186:189], v[6:9]
	v_mfma_f32_16x16x32_bf16 v[2:5], v[210:213], v[186:189], v[2:5]
	v_mfma_f32_16x16x32_bf16 v[38:41], v[218:221], v[166:169], v[34:37]
	v_mfma_f32_16x16x32_bf16 v[22:25], v[206:209], v[182:185], v[22:25]
	v_mfma_f32_16x16x32_bf16 v[18:21], v[218:221], v[182:185], v[18:21]
	v_mfma_f32_16x16x32_bf16 v[6:9], v[206:209], v[190:193], v[6:9]
	v_mfma_f32_16x16x32_bf16 v[2:5], v[218:221], v[190:193], v[2:5]
	s_barrier
	s_setprio 0
	s_add_i32 s57, s57, 2
	s_addk_i32 s55, 0x100
	s_addk_i32 s56, 0x100
	s_cmp_gt_u32 s57, 5
	s_cbranch_scc0 .LBB0_903
	s_mov_b32 m0, s41
	s_nop 0
	buffer_load_dwordx4 v0, s[16:19], s59 offen lds
	s_mov_b32 m0, s33
	s_nop 0
	buffer_load_dwordx4 v214, s[16:19], s59 offen lds
	v_readlane_b32 s8, v251, 45
	v_readlane_b32 s9, v251, 46
	s_and_b64 vcc, exec, s[8:9]
	s_cbranch_vccz .LBB0_906
	s_barrier

; #define PG8_WAIT_V(n) asm volatile("s_waitcnt vmcnt(" #n ")" ::: "memory")
; template <class Epi, bool ALIGN_EPI, bool SP2, class Hook>
; __device__ __forceinline__ void gemm_phase(LAS unsigned char* lds, const Gemm g, const StaticOrder& S, const Epi& E, Acc& acc, const bool fresh, const Hook& H, const int wave_id) {
;     ...
;         for (int t = t0; t < nt; t += 2) {
;             const bool last = (t == nt - 2);
;             const Src a1 = cA + (size_t)(t + 1) * kstep;
;             const Src a2 = last ? nA : cA + (size_t)(t + 2) * kstep, b2 = last ? nB : cB + (size_t)(t + 2) * kstep;
;             const Src a3 = a2 + kstep, b3 = b2 + kstep;
;             if (last && has_next) H(nxt);
;             if constexpr (SP2) {
;             PG8_TRIP_SP2(PG8_WAIT_V(8));
.LBB0_1235:
	s_add_i32 s100, s2, 0xfffc0000
	v_add_u32_e32 v142, 0x10000, v161
	v_add_u32_e32 v163, 0x14000, v161
	ds_read_b128 v[130:133], v142
	ds_read_b128 v[134:137], v142 offset:1024
	ds_read_b128 v[138:141], v142 offset:2048
	ds_read_b128 v[142:145], v142 offset:3072
	ds_read_b128 v[146:149], v163
	ds_read_b128 v[150:153], v163 offset:1024
	ds_read_b128 v[154:157], v163 offset:2048
	ds_read_b128 v[164:167], v163 offset:3072
	s_mov_b32 m0, s41
	s_nop 0
	buffer_load_dwordx4 v0, s[12:15], s100 offen lds
	s_mov_b32 m0, s33
	s_nop 0
	buffer_load_dwordx4 v159, s[12:15], s100 offen lds
	s_mov_b32 m0, s45
	ds_read_b128 v[168:171], v162
	ds_read_b128 v[172:175], v162 offset:1024
	ds_read_b128 v[176:179], v162 offset:2048
	ds_read_b128 v[180:183], v162 offset:3072
	ds_read_b128 v[184:187], v162 offset:4096
	ds_read_b128 v[188:191], v162 offset:5120
	ds_read_b128 v[192:195], v162 offset:6144
	ds_read_b128 v[200:203], v162 offset:7168
	buffer_load_dwordx4 v0, s[12:15], s2 offen lds
	s_mov_b32 m0, s46
	s_nop 0
	buffer_load_dwordx4 v159, s[12:15], s2 offen lds
	s_waitcnt vmcnt(4)
	s_waitcnt lgkmcnt(0)
	s_setprio 1
	s_barrier
	v_mfma_f32_16x16x32_bf16 v[126:129], v[130:133], v[168:171], v[126:129]
	v_mfma_f32_16x16x32_bf16 v[122:125], v[138:141], v[168:171], v[122:125]
	v_mfma_f32_16x16x32_bf16 v[110:113], v[130:133], v[176:179], v[110:113]
	v_mfma_f32_16x16x32_bf16 v[106:109], v[138:141], v[176:179], v[106:109]
	v_mfma_f32_16x16x32_bf16 v[94:97], v[130:133], v[184:187], v[94:97]
	v_mfma_f32_16x16x32_bf16 v[90:93], v[138:141], v[184:187], v[90:93]
	v_mfma_f32_16x16x32_bf16 v[78:81], v[130:133], v[192:195], v[78:81]
	v_mfma_f32_16x16x32_bf16 v[74:77], v[138:141], v[192:195], v[74:77]
	v_mfma_f32_16x16x32_bf16 v[126:129], v[134:137], v[172:175], v[126:129]
	v_mfma_f32_16x16x32_bf16 v[122:125], v[142:145], v[172:175], v[122:125]
	v_mfma_f32_16x16x32_bf16 v[110:113], v[134:137], v[180:183], v[110:113]
	v_mfma_f32_16x16x32_bf16 v[106:109], v[142:145], v[180:183], v[106:109]
	v_mfma_f32_16x16x32_bf16 v[94:97], v[134:137], v[188:191], v[94:97]
	v_mfma_f32_16x16x32_bf16 v[90:93], v[142:145], v[188:191], v[90:93]
	v_mfma_f32_16x16x32_bf16 v[78:81], v[134:137], v[200:203], v[78:81]
	v_mfma_f32_16x16x32_bf16 v[74:77], v[142:145], v[200:203], v[74:77]
	v_mfma_f32_16x16x32_bf16 v[118:121], v[146:149], v[168:171], v[118:121]
	v_mfma_f32_16x16x32_bf16 v[114:117], v[154:157], v[168:171], v[114:117]
	v_mfma_f32_16x16x32_bf16 v[102:105], v[146:149], v[176:179], v[102:105]
	v_mfma_f32_16x16x32_bf16 v[98:101], v[154:157], v[176:179], v[98:101]
	v_mfma_f32_16x16x32_bf16 v[86:89], v[146:149], v[184:187], v[86:89]
	v_mfma_f32_16x16x32_bf16 v[82:85], v[154:157], v[184:187], v[82:85]
	v_mfma_f32_16x16x32_bf16 v[70:73], v[146:149], v[192:195], v[70:73]
	v_mfma_f32_16x16x32_bf16 v[66:69], v[154:157], v[192:195], v[66:69]
	v_mfma_f32_16x16x32_bf16 v[118:121], v[150:153], v[172:175], v[118:121]
	v_mfma_f32_16x16x32_bf16 v[114:117], v[164:167], v[172:175], v[114:117]
	v_mfma_f32_16x16x32_bf16 v[102:105], v[150:153], v[180:183], v[102:105]
	v_mfma_f32_16x16x32_bf16 v[98:101], v[164:167], v[180:183], v[98:101]
	v_mfma_f32_16x16x32_bf16 v[86:89], v[150:153], v[188:191], v[86:89]
	v_mfma_f32_16x16x32_bf16 v[82:85], v[164:167], v[188:191], v[82:85]
	v_mfma_f32_16x16x32_bf16 v[70:73], v[150:153], v[200:203], v[70:73]
	v_mfma_f32_16x16x32_bf16 v[66:69], v[164:167], v[200:203], v[66:69]
	s_barrier
	s_setprio 0
	s_add_i32 s16, s2, 0xfffc0080
	s_cmp_eq_u32 s59, 12
	s_cselect_b32 s62, s55, s16
	s_cselect_b32 s17, s31, s9
	s_cselect_b32 s16, s30, s8
	s_cselect_b32 s19, s35, s51
	s_cselect_b32 s18, s34, s50
	s_cselect_b32 s60, s56, s3
	s_cselect_b32 s20, s26, s12
	s_cselect_b32 s21, s27, s13
	s_cselect_b32 s22, s28, s14
	s_cselect_b32 s23, s29, s15
	s_or_b32 s61, s62, 0x80
	s_mov_b32 m0, s92
	ds_read_b128 v[168:171], v162 offset:16384
	ds_read_b128 v[172:175], v162 offset:17408
	ds_read_b128 v[176:179], v162 offset:18432
	ds_read_b128 v[180:183], v162 offset:19456
	ds_read_b128 v[184:187], v162 offset:20480
	ds_read_b128 v[188:191], v162 offset:21504
	ds_read_b128 v[192:195], v162 offset:22528
	ds_read_b128 v[200:203], v162 offset:23552
	v_add_u32_e32 v196, 0x1c000, v161
	ds_read_b128 v[206:209], v196
	ds_read_b128 v[210:213], v196 offset:1024
	ds_read_b128 v[214:217], v196 offset:2048
	ds_read_b128 v[218:221], v196 offset:3072
	buffer_load_dwordx4 v158, s[16:19], s60 offen lds
	s_mov_b32 m0, s93
	s_add_i32 s63, s60, 0x40000
	buffer_load_dwordx4 v160, s[16:19], s60 offen lds
	s_mov_b32 m0, s94
	s_nop 0
	buffer_load_dwordx4 v158, s[16:19], s63 offen lds
	s_mov_b32 m0, s95
	s_nop 0
	buffer_load_dwordx4 v160, s[16:19], s63 offen lds
	s_waitcnt vmcnt(6)
	s_waitcnt lgkmcnt(0)
	s_setprio 1
	s_barrier
	v_mfma_f32_16x16x32_bf16 v[62:65], v[130:133], v[168:171], v[62:65]
	v_mfma_f32_16x16x32_bf16 v[58:61], v[138:141], v[168:171], v[58:61]
	v_mfma_f32_16x16x32_bf16 v[46:49], v[130:133], v[176:179], v[46:49]
	v_mfma_f32_16x16x32_bf16 v[42:45], v[138:141], v[176:179], v[42:45]
	v_mfma_f32_16x16x32_bf16 v[30:33], v[130:133], v[184:187], v[30:33]
	v_mfma_f32_16x16x32_bf16 v[26:29], v[138:141], v[184:187], v[26:29]
	v_mfma_f32_16x16x32_bf16 v[14:17], v[130:133], v[192:195], v[14:17]
	v_mfma_f32_16x16x32_bf16 v[10:13], v[138:141], v[192:195], v[10:13]
	v_mfma_f32_16x16x32_bf16 v[62:65], v[134:137], v[172:175], v[62:65]
	v_mfma_f32_16x16x32_bf16 v[58:61], v[142:145], v[172:175], v[58:61]
	v_mfma_f32_16x16x32_bf16 v[46:49], v[134:137], v[180:183], v[46:49]
	v_mfma_f32_16x16x32_bf16 v[42:45], v[142:145], v[180:183], v[42:45]
	v_mfma_f32_16x16x32_bf16 v[30:33], v[134:137], v[188:191], v[30:33]
	v_mfma_f32_16x16x32_bf16 v[26:29], v[142:145], v[188:191], v[26:29]
	v_mfma_f32_16x16x32_bf16 v[14:17], v[134:137], v[200:203], v[14:17]
	v_mfma_f32_16x16x32_bf16 v[10:13], v[142:145], v[200:203], v[10:13]
	v_mfma_f32_16x16x32_bf16 v[54:57], v[146:149], v[168:171], v[54:57]
	v_mfma_f32_16x16x32_bf16 v[50:53], v[154:157], v[168:171], v[50:53]
	v_mfma_f32_16x16x32_bf16 v[38:41], v[146:149], v[176:179], v[38:41]
	v_mfma_f32_16x16x32_bf16 v[34:37], v[154:157], v[176:179], v[34:37]
	v_mfma_f32_16x16x32_bf16 v[22:25], v[146:149], v[184:187], v[22:25]
	v_mfma_f32_16x16x32_bf16 v[18:21], v[154:157], v[184:187], v[18:21]
	v_mfma_f32_16x16x32_bf16 v[6:9], v[146:149], v[192:195], v[6:9]
	v_mfma_f32_16x16x32_bf16 v[2:5], v[154:157], v[192:195], v[2:5]
	v_mfma_f32_16x16x32_bf16 v[54:57], v[150:153], v[172:175], v[54:57]
	v_mfma_f32_16x16x32_bf16 v[50:53], v[164:167], v[172:175], v[50:53]
	v_mfma_f32_16x16x32_bf16 v[38:41], v[150:153], v[180:183], v[38:41]
	v_mfma_f32_16x16x32_bf16 v[34:37], v[164:167], v[180:183], v[34:37]
	v_mfma_f32_16x16x32_bf16 v[22:25], v[150:153], v[188:191], v[22:25]
	v_mfma_f32_16x16x32_bf16 v[18:21], v[164:167], v[188:191], v[18:21]
	v_mfma_f32_16x16x32_bf16 v[6:9], v[150:153], v[200:203], v[6:9]
	v_mfma_f32_16x16x32_bf16 v[2:5], v[164:167], v[200:203], v[2:5]
	s_barrier
	s_setprio 0
	s_mov_b32 m0, s44
	s_nop 0
	buffer_load_dwordx4 v0, s[20:23], s62 offen lds
	s_mov_b32 m0, s36
	s_nop 0
	buffer_load_dwordx4 v159, s[20:23], s62 offen lds
	v_add_u32_e32 v142, 0x18000, v161
	v_add_u32_e32 v163, 0x1c000, v161
	ds_read_b128 v[130:133], v142
	ds_read_b128 v[134:137], v142 offset:1024
	ds_read_b128 v[138:141], v142 offset:2048
	ds_read_b128 v[142:145], v142 offset:3072
	s_add_i32 s62, s62, 0x40000
	s_mov_b32 m0, s37
	ds_read_b128 v[168:171], v162 offset:32768
	ds_read_b128 v[172:175], v162 offset:33792
	ds_read_b128 v[176:179], v162 offset:34816
	ds_read_b128 v[180:183], v162 offset:35840
	ds_read_b128 v[184:187], v162 offset:36864
	ds_read_b128 v[188:191], v162 offset:37888
	ds_read_b128 v[192:195], v162 offset:38912
	ds_read_b128 v[200:203], v162 offset:39936
	buffer_load_dwordx4 v0, s[20:23], s62 offen lds
	s_mov_b32 m0, s38
	s_nop 0
	buffer_load_dwordx4 v159, s[20:23], s62 offen lds
	s_waitcnt vmcnt(8)
	s_waitcnt lgkmcnt(0)
	s_setprio 1
	s_barrier
	v_mfma_f32_16x16x32_bf16 v[126:129], v[130:133], v[168:171], v[126:129]
	v_mfma_f32_16x16x32_bf16 v[122:125], v[138:141], v[168:171], v[122:125]
	v_mfma_f32_16x16x32_bf16 v[110:113], v[130:133], v[176:179], v[110:113]
	v_mfma_f32_16x16x32_bf16 v[106:109], v[138:141], v[176:179], v[106:109]
	v_mfma_f32_16x16x32_bf16 v[94:97], v[130:133], v[184:187], v[94:97]
	v_mfma_f32_16x16x32_bf16 v[90:93], v[138:141], v[184:187], v[90:93]
	v_mfma_f32_16x16x32_bf16 v[78:81], v[130:133], v[192:195], v[78:81]
	v_mfma_f32_16x16x32_bf16 v[74:77], v[138:141], v[192:195], v[74:77]
	v_mfma_f32_16x16x32_bf16 v[126:129], v[134:137], v[172:175], v[126:129]
	v_mfma_f32_16x16x32_bf16 v[122:125], v[142:145], v[172:175], v[122:125]
	v_mfma_f32_16x16x32_bf16 v[110:113], v[134:137], v[180:183], v[110:113]
	v_mfma_f32_16x16x32_bf16 v[106:109], v[142:145], v[180:183], v[106:109]
	v_mfma_f32_16x16x32_bf16 v[94:97], v[134:137], v[188:191], v[94:97]
	v_mfma_f32_16x16x32_bf16 v[90:93], v[142:145], v[188:191], v[90:93]
	v_mfma_f32_16x16x32_bf16 v[78:81], v[134:137], v[200:203], v[78:81]
	v_mfma_f32_16x16x32_bf16 v[74:77], v[142:145], v[200:203], v[74:77]
	v_mfma_f32_16x16x32_bf16 v[118:121], v[206:209], v[168:171], v[118:121]
	v_mfma_f32_16x16x32_bf16 v[114:117], v[214:217], v[168:171], v[114:117]
	v_mfma_f32_16x16x32_bf16 v[102:105], v[206:209], v[176:179], v[102:105]
	v_mfma_f32_16x16x32_bf16 v[98:101], v[214:217], v[176:179], v[98:101]
	v_mfma_f32_16x16x32_bf16 v[86:89], v[206:209], v[184:187], v[86:89]
	v_mfma_f32_16x16x32_bf16 v[82:85], v[214:217], v[184:187], v[82:85]
	v_mfma_f32_16x16x32_bf16 v[70:73], v[206:209], v[192:195], v[70:73]
	v_mfma_f32_16x16x32_bf16 v[66:69], v[214:217], v[192:195], v[66:69]
	v_mfma_f32_16x16x32_bf16 v[118:121], v[210:213], v[172:175], v[118:121]
	v_mfma_f32_16x16x32_bf16 v[114:117], v[218:221], v[172:175], v[114:117]
	v_mfma_f32_16x16x32_bf16 v[102:105], v[210:213], v[180:183], v[102:105]
	v_mfma_f32_16x16x32_bf16 v[98:101], v[218:221], v[180:183], v[98:101]
	v_mfma_f32_16x16x32_bf16 v[86:89], v[210:213], v[188:191], v[86:89]
	v_mfma_f32_16x16x32_bf16 v[82:85], v[218:221], v[188:191], v[82:85]
	v_mfma_f32_16x16x32_bf16 v[70:73], v[210:213], v[200:203], v[70:73]
	v_mfma_f32_16x16x32_bf16 v[66:69], v[218:221], v[200:203], v[66:69]
	s_barrier
; #define PG8_STAGE(bufoff, gbase, voff) do { const Src _g = (gbase); _Pragma("unroll") for (int _i = 0; _i < 2; ++_i) \
;         __builtin_amdgcn_raw_ptr_buffer_load_lds(_g.r, (LAS unsigned*)(lds + (bufoff) + ldsw + _i * 8192), 16, (voff)[_i], _g.o, 0, 0); } while (0)
; #define PG8_WAIT_V(n) asm volatile("s_waitcnt vmcnt(" #n ")" ::: "memory")
; template <class Epi, bool ALIGN_EPI, bool SP2, class Hook>
; __device__ __forceinline__ void gemm_phase(LAS unsigned char* lds, const Gemm g, const StaticOrder& S, const Epi& E, Acc& acc, const bool fresh, const Hook& H, const int wave_id) {
;     ...
;         for (int t = t0; t < nt; t += 2) {
;             const bool last = (t == nt - 2);
;             const Src a1 = cA + (size_t)(t + 1) * kstep;
;             const Src a2 = last ? nA : cA + (size_t)(t + 2) * kstep, b2 = last ? nB : cB + (size_t)(t + 2) * kstep;
;             const Src a3 = a2 + kstep, b3 = b2 + kstep;
;             if (last && has_next) H(nxt);
;             if constexpr (SP2) {
;             PG8_TRIP_SP2(PG8_WAIT_V(8));
;             } else {
;             PG8_LDB(B0, 0, 0); PG8_SCHED; PG8_LDA(At, 0, 0); PG8_STAGE(PG8_SA(1, 1), a1 + hstepA, voffA);
;             PG8_WAIT_L(8); PG8_BAR; PG8_WAIT_L(0); PG8_MMA(0, 0, At, B0); PG8_BAR; PG8_SCHED;
;             PG8_LDB(B1, 0, 1); PG8_STAGE(PG8_SB(0, 0), b2, voffB);
;             PG8_BAR; PG8_WAIT_L(0); PG8_MMA(0, 1, At, B1); PG8_BAR;
;             PG8_LDA(At, 0, 1); PG8_STAGE(PG8_SA(0, 0), a2, voffA);
;             PG8_BAR; PG8_WAIT_L(0); PG8_MMA(1, 0, At, B0); PG8_BAR; PG8_SCHED;
;             PG8_STAGE(PG8_SB(0, 1), b2 + hstep, voffB);
;             PG8_WAIT_V(6); PG8_BAR; PG8_MMA(1, 1, At, B1); PG8_BAR;
;             PG8_LDB(B0, 1, 0); PG8_SCHED; PG8_LDA(At, 1, 0); PG8_STAGE(PG8_SA(0, 1), a2 + hstepA, voffA);
;             PG8_WAIT_L(8); PG8_BAR; PG8_WAIT_L(0); PG8_MMA(0, 0, At, B0); PG8_BAR; PG8_SCHED;
;             PG8_LDB(B1, 1, 1); PG8_STAGE(PG8_SB(1, 0), b3, voffB);
;             PG8_BAR; PG8_WAIT_L(0); PG8_MMA(0, 1, At, B1); PG8_BAR;
;             PG8_LDA(At, 1, 1); PG8_STAGE(PG8_SA(1, 0), a3, voffA);
;             PG8_BAR; PG8_WAIT_L(0); PG8_MMA(1, 0, At, B0); PG8_BAR; PG8_SCHED;
;             PG8_STAGE(PG8_SB(1, 1), b3 + hstep, voffB);
;             PG8_WAIT_V(6); PG8_BAR; PG8_MMA(1, 1, At, B1); PG8_BAR;
;             }
;         }
;         if constexpr (ALIGN_EPI) { if (wr == 0) PG8_BAR; }
	s_setprio 0
	s_mov_b32 m0, s39
	s_or_b32 s62, s60, 0x80
	ds_read_b128 v[168:171], v162 offset:49152
	ds_read_b128 v[172:175], v162 offset:50176
	ds_read_b128 v[176:179], v162 offset:51200
	ds_read_b128 v[180:183], v162 offset:52224
	ds_read_b128 v[184:187], v162 offset:53248
	ds_read_b128 v[188:191], v162 offset:54272
	ds_read_b128 v[192:195], v162 offset:55296
	ds_read_b128 v[200:203], v162 offset:56320
	buffer_load_dwordx4 v158, s[16:19], s62 offen lds
	s_mov_b32 m0, s40
	s_add_i32 s60, s60, 0x40080
	buffer_load_dwordx4 v160, s[16:19], s62 offen lds
	s_mov_b32 m0, s43
	s_nop 0
	buffer_load_dwordx4 v158, s[16:19], s60 offen lds
	s_mov_b32 m0, s42
	s_nop 0
	buffer_load_dwordx4 v160, s[16:19], s60 offen lds
	s_waitcnt vmcnt(6)
	s_waitcnt lgkmcnt(0)
	s_setprio 1
	s_barrier
	v_mfma_f32_16x16x32_bf16 v[62:65], v[130:133], v[168:171], v[62:65]
	v_mfma_f32_16x16x32_bf16 v[58:61], v[138:141], v[168:171], v[58:61]
	v_mfma_f32_16x16x32_bf16 v[46:49], v[130:133], v[176:179], v[46:49]
	v_mfma_f32_16x16x32_bf16 v[42:45], v[138:141], v[176:179], v[42:45]
	v_mfma_f32_16x16x32_bf16 v[30:33], v[130:133], v[184:187], v[30:33]
	v_mfma_f32_16x16x32_bf16 v[26:29], v[138:141], v[184:187], v[26:29]
	v_mfma_f32_16x16x32_bf16 v[14:17], v[130:133], v[192:195], v[14:17]
	v_mfma_f32_16x16x32_bf16 v[10:13], v[138:141], v[192:195], v[10:13]
	v_mfma_f32_16x16x32_bf16 v[62:65], v[134:137], v[172:175], v[62:65]
	v_mfma_f32_16x16x32_bf16 v[58:61], v[142:145], v[172:175], v[58:61]
	v_mfma_f32_16x16x32_bf16 v[46:49], v[134:137], v[180:183], v[46:49]
	v_mfma_f32_16x16x32_bf16 v[42:45], v[142:145], v[180:183], v[42:45]
	v_mfma_f32_16x16x32_bf16 v[30:33], v[134:137], v[188:191], v[30:33]
	v_mfma_f32_16x16x32_bf16 v[26:29], v[142:145], v[188:191], v[26:29]
	v_mfma_f32_16x16x32_bf16 v[14:17], v[134:137], v[200:203], v[14:17]
	v_mfma_f32_16x16x32_bf16 v[10:13], v[142:145], v[200:203], v[10:13]
	v_mfma_f32_16x16x32_bf16 v[54:57], v[206:209], v[168:171], v[54:57]
	v_mfma_f32_16x16x32_bf16 v[50:53], v[214:217], v[168:171], v[50:53]
	v_mfma_f32_16x16x32_bf16 v[38:41], v[206:209], v[176:179], v[38:41]
	v_mfma_f32_16x16x32_bf16 v[34:37], v[214:217], v[176:179], v[34:37]
	v_mfma_f32_16x16x32_bf16 v[22:25], v[206:209], v[184:187], v[22:25]
	v_mfma_f32_16x16x32_bf16 v[18:21], v[214:217], v[184:187], v[18:21]
	v_mfma_f32_16x16x32_bf16 v[6:9], v[206:209], v[192:195], v[6:9]
	v_mfma_f32_16x16x32_bf16 v[2:5], v[214:217], v[192:195], v[2:5]
	v_mfma_f32_16x16x32_bf16 v[54:57], v[210:213], v[172:175], v[54:57]
	v_mfma_f32_16x16x32_bf16 v[50:53], v[218:221], v[172:175], v[50:53]
	v_mfma_f32_16x16x32_bf16 v[38:41], v[210:213], v[180:183], v[38:41]
	v_mfma_f32_16x16x32_bf16 v[34:37], v[218:221], v[180:183], v[34:37]
	v_mfma_f32_16x16x32_bf16 v[22:25], v[210:213], v[188:191], v[22:25]
	v_mfma_f32_16x16x32_bf16 v[18:21], v[218:221], v[188:191], v[18:21]
	v_mfma_f32_16x16x32_bf16 v[6:9], v[210:213], v[200:203], v[6:9]
	v_mfma_f32_16x16x32_bf16 v[2:5], v[218:221], v[200:203], v[2:5]
	s_barrier
	s_setprio 0
	s_add_i32 s59, s59, 2
	s_addk_i32 s2, 0x100
	s_addk_i32 s3, 0x100
	s_cmp_gt_u32 s59, 13
	s_cbranch_scc0 .LBB0_1235
	s_mov_b32 m0, s41
	s_nop 0
	buffer_load_dwordx4 v0, s[20:23], s61 offen lds
	s_mov_b32 m0, s33
	s_nop 0
	buffer_load_dwordx4 v159, s[20:23], s61 offen lds
	v_readlane_b32 s2, v251, 45
	v_readlane_b32 s3, v251, 46
	s_and_b64 vcc, exec, s[2:3]
	s_cbranch_vccz .LBB0_1238
	s_barrier

; #define PG8_WAIT_V(n) asm volatile("s_waitcnt vmcnt(" #n ")" ::: "memory")
; template <class Epi, bool ALIGN_EPI, bool SP2, class Hook>
; __device__ __forceinline__ void gemm_phase(LAS unsigned char* lds, const Gemm g, const StaticOrder& S, const Epi& E, Acc& acc, const bool fresh, const Hook& H, const int wave_id) {
;     ...
;         for (int t = t0; t < nt; t += 2) {
;             const bool last = (t == nt - 2);
;             const Src a1 = cA + (size_t)(t + 1) * kstep;
;             const Src a2 = last ? nA : cA + (size_t)(t + 2) * kstep, b2 = last ? nB : cB + (size_t)(t + 2) * kstep;
;             const Src a3 = a2 + kstep, b3 = b2 + kstep;
;             if (last && has_next) H(nxt);
;             if constexpr (SP2) {
;             PG8_TRIP_SP2(PG8_WAIT_V(8));
.LBB0_1461:
	s_add_i32 s100, s55, 0xfffc0000
	v_add_u32_e32 v138, 0x10000, v136
	v_add_u32_e32 v139, 0x14000, v136
	ds_read_b128 v[140:143], v138
	ds_read_b128 v[144:147], v138 offset:1024
	ds_read_b128 v[148:151], v138 offset:2048
	ds_read_b128 v[152:155], v138 offset:3072
	ds_read_b128 v[156:159], v139
	ds_read_b128 v[160:163], v139 offset:1024
	ds_read_b128 v[164:167], v139 offset:2048
	ds_read_b128 v[168:171], v139 offset:3072
	s_mov_b32 m0, s41
	s_nop 0
	buffer_load_dwordx4 v132, s[12:15], s100 offen lds
	s_mov_b32 m0, s33
	s_nop 0
	buffer_load_dwordx4 v134, s[12:15], s100 offen lds
	s_mov_b32 m0, s45
	ds_read_b128 v[172:175], v137
	ds_read_b128 v[176:179], v137 offset:1024
	ds_read_b128 v[180:183], v137 offset:2048
	ds_read_b128 v[184:187], v137 offset:3072
	ds_read_b128 v[188:191], v137 offset:4096
	ds_read_b128 v[192:195], v137 offset:5120
	ds_read_b128 v[200:203], v137 offset:6144
	ds_read_b128 v[204:207], v137 offset:7168
	buffer_load_dwordx4 v132, s[12:15], s55 offen lds
	s_mov_b32 m0, s46
	s_nop 0
	buffer_load_dwordx4 v134, s[12:15], s55 offen lds
	s_waitcnt vmcnt(4)
	s_waitcnt lgkmcnt(0)
	s_setprio 1
	s_barrier
	v_mfma_f32_16x16x32_bf16 v[124:127], v[140:143], v[172:175], v[124:127]
	v_mfma_f32_16x16x32_bf16 v[116:119], v[148:151], v[172:175], v[116:119]
	v_mfma_f32_16x16x32_bf16 v[108:111], v[140:143], v[180:183], v[108:111]
	v_mfma_f32_16x16x32_bf16 v[100:103], v[148:151], v[180:183], v[100:103]
	v_mfma_f32_16x16x32_bf16 v[92:95], v[140:143], v[188:191], v[92:95]
	v_mfma_f32_16x16x32_bf16 v[84:87], v[148:151], v[188:191], v[84:87]
	v_mfma_f32_16x16x32_bf16 v[76:79], v[140:143], v[200:203], v[76:79]
	v_mfma_f32_16x16x32_bf16 v[64:67], v[148:151], v[200:203], v[64:67]
	v_mfma_f32_16x16x32_bf16 v[124:127], v[144:147], v[176:179], v[124:127]
	v_mfma_f32_16x16x32_bf16 v[116:119], v[152:155], v[176:179], v[116:119]
	v_mfma_f32_16x16x32_bf16 v[108:111], v[144:147], v[184:187], v[108:111]
	v_mfma_f32_16x16x32_bf16 v[100:103], v[152:155], v[184:187], v[100:103]
	v_mfma_f32_16x16x32_bf16 v[92:95], v[144:147], v[192:195], v[92:95]
	v_mfma_f32_16x16x32_bf16 v[84:87], v[152:155], v[192:195], v[84:87]
	v_mfma_f32_16x16x32_bf16 v[76:79], v[144:147], v[204:207], v[76:79]
	v_mfma_f32_16x16x32_bf16 v[64:67], v[152:155], v[204:207], v[64:67]
	v_mfma_f32_16x16x32_bf16 v[128:131], v[156:159], v[172:175], v[128:131]
	v_mfma_f32_16x16x32_bf16 v[120:123], v[164:167], v[172:175], v[120:123]
	v_mfma_f32_16x16x32_bf16 v[112:115], v[156:159], v[180:183], v[112:115]
	v_mfma_f32_16x16x32_bf16 v[104:107], v[164:167], v[180:183], v[104:107]
	v_mfma_f32_16x16x32_bf16 v[96:99], v[156:159], v[188:191], v[96:99]
	v_mfma_f32_16x16x32_bf16 v[88:91], v[164:167], v[188:191], v[88:91]
	v_mfma_f32_16x16x32_bf16 v[80:83], v[156:159], v[200:203], v[80:83]
	v_mfma_f32_16x16x32_bf16 v[68:71], v[164:167], v[200:203], v[68:71]
	v_mfma_f32_16x16x32_bf16 v[128:131], v[160:163], v[176:179], v[128:131]
	v_mfma_f32_16x16x32_bf16 v[120:123], v[168:171], v[176:179], v[120:123]
	v_mfma_f32_16x16x32_bf16 v[112:115], v[160:163], v[184:187], v[112:115]
	v_mfma_f32_16x16x32_bf16 v[104:107], v[168:171], v[184:187], v[104:107]
	v_mfma_f32_16x16x32_bf16 v[96:99], v[160:163], v[192:195], v[96:99]
	v_mfma_f32_16x16x32_bf16 v[88:91], v[168:171], v[192:195], v[88:91]
	v_mfma_f32_16x16x32_bf16 v[80:83], v[160:163], v[204:207], v[80:83]
	v_mfma_f32_16x16x32_bf16 v[68:71], v[168:171], v[204:207], v[68:71]
	s_barrier
	s_setprio 0
	s_add_i32 s16, s55, 0xfffc0080
	s_cmp_eq_u32 s54, 12
	s_cselect_b32 s59, s50, s16
	s_cselect_b32 s17, s9, s77
	s_cselect_b32 s16, s8, s76
	s_cselect_b32 s19, s11, s29
	s_cselect_b32 s18, s10, s28
	s_cselect_b32 s57, s51, s56
	s_cselect_b32 s20, s4, s12
	s_cselect_b32 s21, s5, s13
	s_cselect_b32 s22, s6, s14
	s_cselect_b32 s23, s7, s15
	s_or_b32 s58, s59, 0x80
	s_mov_b32 m0, s92
	ds_read_b128 v[172:175], v137 offset:16384
	ds_read_b128 v[176:179], v137 offset:17408
	ds_read_b128 v[180:183], v137 offset:18432
	ds_read_b128 v[184:187], v137 offset:19456
	ds_read_b128 v[188:191], v137 offset:20480
	ds_read_b128 v[192:195], v137 offset:21504
	ds_read_b128 v[200:203], v137 offset:22528
	ds_read_b128 v[204:207], v137 offset:23552
	v_add_u32_e32 v199, 0x1c000, v136
	ds_read_b128 v[208:211], v199
	ds_read_b128 v[212:215], v199 offset:1024
	ds_read_b128 v[216:219], v199 offset:2048
	ds_read_b128 v[220:223], v199 offset:3072
	buffer_load_dwordx4 v133, s[16:19], s57 offen lds
	s_mov_b32 m0, s93
	s_add_i32 s60, s57, 0x40000
	buffer_load_dwordx4 v135, s[16:19], s57 offen lds
	s_mov_b32 m0, s94
	s_nop 0
	buffer_load_dwordx4 v133, s[16:19], s60 offen lds
	s_mov_b32 m0, s95
	s_nop 0
	buffer_load_dwordx4 v135, s[16:19], s60 offen lds
	s_waitcnt vmcnt(6)
	s_waitcnt lgkmcnt(0)
	s_setprio 1
	s_barrier
	v_mfma_f32_16x16x32_bf16 v[60:63], v[140:143], v[172:175], v[60:63]
	v_mfma_f32_16x16x32_bf16 v[52:55], v[148:151], v[172:175], v[52:55]
	v_mfma_f32_16x16x32_bf16 v[44:47], v[140:143], v[180:183], v[44:47]
	v_mfma_f32_16x16x32_bf16 v[36:39], v[148:151], v[180:183], v[36:39]
	v_mfma_f32_16x16x32_bf16 v[28:31], v[140:143], v[188:191], v[28:31]
	v_mfma_f32_16x16x32_bf16 v[20:23], v[148:151], v[188:191], v[20:23]
	v_mfma_f32_16x16x32_bf16 v[12:15], v[140:143], v[200:203], v[12:15]
	v_mfma_f32_16x16x32_bf16 v[2:5], v[148:151], v[200:203], v[4:7]
	v_mfma_f32_16x16x32_bf16 v[60:63], v[144:147], v[176:179], v[60:63]
	v_mfma_f32_16x16x32_bf16 v[52:55], v[152:155], v[176:179], v[52:55]
	v_mfma_f32_16x16x32_bf16 v[44:47], v[144:147], v[184:187], v[44:47]
	v_mfma_f32_16x16x32_bf16 v[36:39], v[152:155], v[184:187], v[36:39]
	v_mfma_f32_16x16x32_bf16 v[28:31], v[144:147], v[192:195], v[28:31]
	v_mfma_f32_16x16x32_bf16 v[20:23], v[152:155], v[192:195], v[20:23]
	v_mfma_f32_16x16x32_bf16 v[12:15], v[144:147], v[204:207], v[12:15]
	v_mfma_f32_16x16x32_bf16 v[2:5], v[152:155], v[204:207], v[2:5]
	v_mfma_f32_16x16x32_bf16 v[72:75], v[156:159], v[172:175], v[72:75]
	v_mfma_f32_16x16x32_bf16 v[56:59], v[164:167], v[172:175], v[56:59]
	v_mfma_f32_16x16x32_bf16 v[48:51], v[156:159], v[180:183], v[48:51]
	v_mfma_f32_16x16x32_bf16 v[40:43], v[164:167], v[180:183], v[40:43]
	v_mfma_f32_16x16x32_bf16 v[32:35], v[156:159], v[188:191], v[32:35]
	v_mfma_f32_16x16x32_bf16 v[24:27], v[164:167], v[188:191], v[24:27]
	v_mfma_f32_16x16x32_bf16 v[16:19], v[156:159], v[200:203], v[16:19]
	v_mfma_f32_16x16x32_bf16 v[6:9], v[164:167], v[200:203], v[8:11]
	v_mfma_f32_16x16x32_bf16 v[72:75], v[160:163], v[176:179], v[72:75]
	v_mfma_f32_16x16x32_bf16 v[56:59], v[168:171], v[176:179], v[56:59]
	v_mfma_f32_16x16x32_bf16 v[48:51], v[160:163], v[184:187], v[48:51]
	v_mfma_f32_16x16x32_bf16 v[40:43], v[168:171], v[184:187], v[40:43]
	v_mfma_f32_16x16x32_bf16 v[32:35], v[160:163], v[192:195], v[32:35]
	v_mfma_f32_16x16x32_bf16 v[24:27], v[168:171], v[192:195], v[24:27]
	v_mfma_f32_16x16x32_bf16 v[16:19], v[160:163], v[204:207], v[16:19]
	v_mfma_f32_16x16x32_bf16 v[8:11], v[168:171], v[204:207], v[6:9]
	s_barrier
	s_setprio 0
	s_mov_b32 m0, s44
	s_nop 0
	buffer_load_dwordx4 v132, s[20:23], s59 offen lds
	s_mov_b32 m0, s36
	s_nop 0
	buffer_load_dwordx4 v134, s[20:23], s59 offen lds
	v_add_u32_e32 v140, 0x18000, v136
	v_add_u32_e32 v141, 0x1c000, v136
	ds_read_b128 v[142:145], v140
	ds_read_b128 v[146:149], v140 offset:1024
	ds_read_b128 v[150:153], v140 offset:2048
	ds_read_b128 v[154:157], v140 offset:3072
	s_add_i32 s59, s59, 0x40000
	s_mov_b32 m0, s37
	ds_read_b128 v[174:177], v137 offset:32768
	ds_read_b128 v[178:181], v137 offset:33792
	ds_read_b128 v[182:185], v137 offset:34816
	ds_read_b128 v[186:189], v137 offset:35840
	ds_read_b128 v[190:193], v137 offset:36864
	ds_read_b128 v[194:197], v137 offset:37888
	ds_read_b128 v[200:203], v137 offset:38912
	ds_read_b128 v[204:207], v137 offset:39936
	buffer_load_dwordx4 v132, s[20:23], s59 offen lds
	s_mov_b32 m0, s38
	s_nop 0
	buffer_load_dwordx4 v134, s[20:23], s59 offen lds
	s_waitcnt vmcnt(8)
	s_waitcnt lgkmcnt(0)
	s_setprio 1
	s_barrier
	v_mfma_f32_16x16x32_bf16 v[124:127], v[142:145], v[174:177], v[124:127]
	v_mfma_f32_16x16x32_bf16 v[116:119], v[150:153], v[174:177], v[116:119]
	v_mfma_f32_16x16x32_bf16 v[108:111], v[142:145], v[182:185], v[108:111]
	v_mfma_f32_16x16x32_bf16 v[100:103], v[150:153], v[182:185], v[100:103]
	v_mfma_f32_16x16x32_bf16 v[92:95], v[142:145], v[190:193], v[92:95]
	v_mfma_f32_16x16x32_bf16 v[84:87], v[150:153], v[190:193], v[84:87]
	v_mfma_f32_16x16x32_bf16 v[76:79], v[142:145], v[200:203], v[76:79]
	v_mfma_f32_16x16x32_bf16 v[64:67], v[150:153], v[200:203], v[64:67]
	v_mfma_f32_16x16x32_bf16 v[124:127], v[146:149], v[178:181], v[124:127]
	v_mfma_f32_16x16x32_bf16 v[116:119], v[154:157], v[178:181], v[116:119]
	v_mfma_f32_16x16x32_bf16 v[108:111], v[146:149], v[186:189], v[108:111]
	v_mfma_f32_16x16x32_bf16 v[100:103], v[154:157], v[186:189], v[100:103]
	v_mfma_f32_16x16x32_bf16 v[92:95], v[146:149], v[194:197], v[92:95]
	v_mfma_f32_16x16x32_bf16 v[84:87], v[154:157], v[194:197], v[84:87]
	v_mfma_f32_16x16x32_bf16 v[76:79], v[146:149], v[204:207], v[76:79]
	v_mfma_f32_16x16x32_bf16 v[64:67], v[154:157], v[204:207], v[64:67]
	v_mfma_f32_16x16x32_bf16 v[128:131], v[208:211], v[174:177], v[128:131]
	v_mfma_f32_16x16x32_bf16 v[120:123], v[216:219], v[174:177], v[120:123]
	v_mfma_f32_16x16x32_bf16 v[112:115], v[208:211], v[182:185], v[112:115]
	v_mfma_f32_16x16x32_bf16 v[104:107], v[216:219], v[182:185], v[104:107]
	v_mfma_f32_16x16x32_bf16 v[96:99], v[208:211], v[190:193], v[96:99]
	v_mfma_f32_16x16x32_bf16 v[88:91], v[216:219], v[190:193], v[88:91]
	v_mfma_f32_16x16x32_bf16 v[80:83], v[208:211], v[200:203], v[80:83]
	v_mfma_f32_16x16x32_bf16 v[68:71], v[216:219], v[200:203], v[68:71]
	v_mfma_f32_16x16x32_bf16 v[128:131], v[212:215], v[178:181], v[128:131]
	v_mfma_f32_16x16x32_bf16 v[120:123], v[220:223], v[178:181], v[120:123]
	v_mfma_f32_16x16x32_bf16 v[112:115], v[212:215], v[186:189], v[112:115]
	v_mfma_f32_16x16x32_bf16 v[104:107], v[220:223], v[186:189], v[104:107]
	v_mfma_f32_16x16x32_bf16 v[96:99], v[212:215], v[194:197], v[96:99]
	v_mfma_f32_16x16x32_bf16 v[88:91], v[220:223], v[194:197], v[88:91]
	v_mfma_f32_16x16x32_bf16 v[80:83], v[212:215], v[204:207], v[80:83]
	v_mfma_f32_16x16x32_bf16 v[68:71], v[220:223], v[204:207], v[68:71]
	s_barrier
; #define PG8_STAGE(bufoff, gbase, voff) do { const Src _g = (gbase); _Pragma("unroll") for (int _i = 0; _i < 2; ++_i) \
;         __builtin_amdgcn_raw_ptr_buffer_load_lds(_g.r, (LAS unsigned*)(lds + (bufoff) + ldsw + _i * 8192), 16, (voff)[_i], _g.o, 0, 0); } while (0)
; #define PG8_WAIT_V(n) asm volatile("s_waitcnt vmcnt(" #n ")" ::: "memory")
; template <class Epi, bool ALIGN_EPI, bool SP2, class Hook>
; __device__ __forceinline__ void gemm_phase(LAS unsigned char* lds, const Gemm g, const StaticOrder& S, const Epi& E, Acc& acc, const bool fresh, const Hook& H, const int wave_id) {
;     ...
;         for (int t = t0; t < nt; t += 2) {
;             const bool last = (t == nt - 2);
;             const Src a1 = cA + (size_t)(t + 1) * kstep;
;             const Src a2 = last ? nA : cA + (size_t)(t + 2) * kstep, b2 = last ? nB : cB + (size_t)(t + 2) * kstep;
;             const Src a3 = a2 + kstep, b3 = b2 + kstep;
;             if (last && has_next) H(nxt);
;             if constexpr (SP2) {
;             PG8_TRIP_SP2(PG8_WAIT_V(8));
;             } else {
;             PG8_LDB(B0, 0, 0); PG8_SCHED; PG8_LDA(At, 0, 0); PG8_STAGE(PG8_SA(1, 1), a1 + hstepA, voffA);
;             PG8_WAIT_L(8); PG8_BAR; PG8_WAIT_L(0); PG8_MMA(0, 0, At, B0); PG8_BAR; PG8_SCHED;
;             PG8_LDB(B1, 0, 1); PG8_STAGE(PG8_SB(0, 0), b2, voffB);
;             PG8_BAR; PG8_WAIT_L(0); PG8_MMA(0, 1, At, B1); PG8_BAR;
;             PG8_LDA(At, 0, 1); PG8_STAGE(PG8_SA(0, 0), a2, voffA);
;             PG8_BAR; PG8_WAIT_L(0); PG8_MMA(1, 0, At, B0); PG8_BAR; PG8_SCHED;
;             PG8_STAGE(PG8_SB(0, 1), b2 + hstep, voffB);
;             PG8_WAIT_V(6); PG8_BAR; PG8_MMA(1, 1, At, B1); PG8_BAR;
;             PG8_LDB(B0, 1, 0); PG8_SCHED; PG8_LDA(At, 1, 0); PG8_STAGE(PG8_SA(0, 1), a2 + hstepA, voffA);
;             PG8_WAIT_L(8); PG8_BAR; PG8_WAIT_L(0); PG8_MMA(0, 0, At, B0); PG8_BAR; PG8_SCHED;
;             PG8_LDB(B1, 1, 1); PG8_STAGE(PG8_SB(1, 0), b3, voffB);
;             PG8_BAR; PG8_WAIT_L(0); PG8_MMA(0, 1, At, B1); PG8_BAR;
;             PG8_LDA(At, 1, 1); PG8_STAGE(PG8_SA(1, 0), a3, voffA);
;             PG8_BAR; PG8_WAIT_L(0); PG8_MMA(1, 0, At, B0); PG8_BAR; PG8_SCHED;
;             PG8_STAGE(PG8_SB(1, 1), b3 + hstep, voffB);
;             PG8_WAIT_V(6); PG8_BAR; PG8_MMA(1, 1, At, B1); PG8_BAR;
;             }
;         }
;         if constexpr (ALIGN_EPI) { if (wr == 0) PG8_BAR; }
	s_setprio 0
	s_mov_b32 m0, s39
	s_or_b32 s59, s57, 0x80
	ds_read_b128 v[174:177], v137 offset:49152
	ds_read_b128 v[178:181], v137 offset:50176
	ds_read_b128 v[182:185], v137 offset:51200
	ds_read_b128 v[186:189], v137 offset:52224
	ds_read_b128 v[190:193], v137 offset:53248
	ds_read_b128 v[194:197], v137 offset:54272
	ds_read_b128 v[200:203], v137 offset:55296
	ds_read_b128 v[204:207], v137 offset:56320
	buffer_load_dwordx4 v133, s[16:19], s59 offen lds
	s_mov_b32 m0, s40
	s_add_i32 s57, s57, 0x40080
	buffer_load_dwordx4 v135, s[16:19], s59 offen lds
	s_mov_b32 m0, s43
	s_nop 0
	buffer_load_dwordx4 v133, s[16:19], s57 offen lds
	s_mov_b32 m0, s42
	s_nop 0
	buffer_load_dwordx4 v135, s[16:19], s57 offen lds
	s_waitcnt vmcnt(6)
	s_waitcnt lgkmcnt(0)
	s_setprio 1
	s_barrier
	v_mfma_f32_16x16x32_bf16 v[60:63], v[142:145], v[174:177], v[60:63]
	v_mfma_f32_16x16x32_bf16 v[52:55], v[150:153], v[174:177], v[52:55]
	v_mfma_f32_16x16x32_bf16 v[44:47], v[142:145], v[182:185], v[44:47]
	v_mfma_f32_16x16x32_bf16 v[36:39], v[150:153], v[182:185], v[36:39]
	v_mfma_f32_16x16x32_bf16 v[28:31], v[142:145], v[190:193], v[28:31]
	v_mfma_f32_16x16x32_bf16 v[20:23], v[150:153], v[190:193], v[20:23]
	v_mfma_f32_16x16x32_bf16 v[12:15], v[142:145], v[200:203], v[12:15]
	v_mfma_f32_16x16x32_bf16 v[2:5], v[150:153], v[200:203], v[2:5]
	v_mfma_f32_16x16x32_bf16 v[60:63], v[146:149], v[178:181], v[60:63]
	v_mfma_f32_16x16x32_bf16 v[52:55], v[154:157], v[178:181], v[52:55]
	v_mfma_f32_16x16x32_bf16 v[44:47], v[146:149], v[186:189], v[44:47]
	v_mfma_f32_16x16x32_bf16 v[36:39], v[154:157], v[186:189], v[36:39]
	v_mfma_f32_16x16x32_bf16 v[28:31], v[146:149], v[194:197], v[28:31]
	v_mfma_f32_16x16x32_bf16 v[20:23], v[154:157], v[194:197], v[20:23]
	v_mfma_f32_16x16x32_bf16 v[12:15], v[146:149], v[204:207], v[12:15]
	v_mfma_f32_16x16x32_bf16 v[4:7], v[154:157], v[204:207], v[2:5]
	v_mfma_f32_16x16x32_bf16 v[72:75], v[208:211], v[174:177], v[72:75]
	v_mfma_f32_16x16x32_bf16 v[56:59], v[216:219], v[174:177], v[56:59]
	v_mfma_f32_16x16x32_bf16 v[48:51], v[208:211], v[182:185], v[48:51]
	v_mfma_f32_16x16x32_bf16 v[40:43], v[216:219], v[182:185], v[40:43]
	v_mfma_f32_16x16x32_bf16 v[32:35], v[208:211], v[190:193], v[32:35]
	v_mfma_f32_16x16x32_bf16 v[24:27], v[216:219], v[190:193], v[24:27]
	v_mfma_f32_16x16x32_bf16 v[16:19], v[208:211], v[200:203], v[16:19]
	v_mfma_f32_16x16x32_bf16 v[8:11], v[216:219], v[200:203], v[8:11]
	v_mfma_f32_16x16x32_bf16 v[72:75], v[212:215], v[178:181], v[72:75]
	v_mfma_f32_16x16x32_bf16 v[56:59], v[220:223], v[178:181], v[56:59]
	v_mfma_f32_16x16x32_bf16 v[48:51], v[212:215], v[186:189], v[48:51]
	v_mfma_f32_16x16x32_bf16 v[40:43], v[220:223], v[186:189], v[40:43]
	v_mfma_f32_16x16x32_bf16 v[32:35], v[212:215], v[194:197], v[32:35]
	v_mfma_f32_16x16x32_bf16 v[24:27], v[220:223], v[194:197], v[24:27]
	v_mfma_f32_16x16x32_bf16 v[16:19], v[212:215], v[204:207], v[16:19]
	v_mfma_f32_16x16x32_bf16 v[8:11], v[220:223], v[204:207], v[8:11]
	s_barrier
	s_setprio 0
	s_add_i32 s54, s54, 2
	s_addk_i32 s55, 0x100
	s_addk_i32 s56, 0x100
	s_cmp_gt_u32 s54, 13
	s_cbranch_scc0 .LBB0_1461
	s_mov_b32 m0, s41
	s_nop 0
	buffer_load_dwordx4 v132, s[20:23], s58 offen lds
	s_mov_b32 m0, s33
	s_nop 0
	buffer_load_dwordx4 v134, s[20:23], s58 offen lds
	v_readlane_b32 s12, v251, 45
	v_readlane_b32 s13, v251, 46
	s_and_b64 vcc, exec, s[12:13]
	s_cbranch_vccz .LBB0_1464
	s_barrier

; #define PG8_WAIT_V(n) asm volatile("s_waitcnt vmcnt(" #n ")" ::: "memory")
; template <class Epi, bool ALIGN_EPI, bool SP2, class Hook>
; __device__ __forceinline__ void gemm_phase(LAS unsigned char* lds, const Gemm g, const StaticOrder& S, const Epi& E, Acc& acc, const bool fresh, const Hook& H, const int wave_id) {
;     ...
;         for (int t = t0; t < nt; t += 2) {
;             const bool last = (t == nt - 2);
;             const Src a1 = cA + (size_t)(t + 1) * kstep;
;             const Src a2 = last ? nA : cA + (size_t)(t + 2) * kstep, b2 = last ? nB : cB + (size_t)(t + 2) * kstep;
;             const Src a3 = a2 + kstep, b3 = b2 + kstep;
;             if (last && has_next) H(nxt);
;             if constexpr (SP2) {
;             PG8_TRIP_SP2(PG8_WAIT_V(8));
.LBB0_1572:
	s_add_i32 s100, s2, 0xfff40000
	v_add_u32_e32 v142, 0x10000, v161
	v_add_u32_e32 v163, 0x14000, v161
	ds_read_b128 v[130:133], v142
	ds_read_b128 v[134:137], v142 offset:1024
	ds_read_b128 v[138:141], v142 offset:2048
	ds_read_b128 v[142:145], v142 offset:3072
	ds_read_b128 v[146:149], v163
	ds_read_b128 v[150:153], v163 offset:1024
	ds_read_b128 v[154:157], v163 offset:2048
	ds_read_b128 v[164:167], v163 offset:3072
	s_mov_b32 m0, s41
	s_nop 0
	buffer_load_dwordx4 v0, s[12:15], s100 offen lds
	s_mov_b32 m0, s33
	s_nop 0
	buffer_load_dwordx4 v159, s[12:15], s100 offen lds
	s_mov_b32 m0, s45
	ds_read_b128 v[168:171], v162
	ds_read_b128 v[172:175], v162 offset:1024
	ds_read_b128 v[176:179], v162 offset:2048
	ds_read_b128 v[180:183], v162 offset:3072
	ds_read_b128 v[184:187], v162 offset:4096
	ds_read_b128 v[188:191], v162 offset:5120
	ds_read_b128 v[192:195], v162 offset:6144
	ds_read_b128 v[200:203], v162 offset:7168
	buffer_load_dwordx4 v0, s[12:15], s2 offen lds
	s_mov_b32 m0, s46
	s_nop 0
	buffer_load_dwordx4 v159, s[12:15], s2 offen lds
	s_waitcnt vmcnt(4)
	s_waitcnt lgkmcnt(0)
	s_setprio 1
	s_barrier
	v_mfma_f32_16x16x32_bf16 v[126:129], v[130:133], v[168:171], v[126:129]
	v_mfma_f32_16x16x32_bf16 v[122:125], v[138:141], v[168:171], v[122:125]
	v_mfma_f32_16x16x32_bf16 v[110:113], v[130:133], v[176:179], v[110:113]
	v_mfma_f32_16x16x32_bf16 v[106:109], v[138:141], v[176:179], v[106:109]
	v_mfma_f32_16x16x32_bf16 v[94:97], v[130:133], v[184:187], v[94:97]
	v_mfma_f32_16x16x32_bf16 v[90:93], v[138:141], v[184:187], v[90:93]
	v_mfma_f32_16x16x32_bf16 v[78:81], v[130:133], v[192:195], v[78:81]
	v_mfma_f32_16x16x32_bf16 v[74:77], v[138:141], v[192:195], v[74:77]
	v_mfma_f32_16x16x32_bf16 v[126:129], v[134:137], v[172:175], v[126:129]
	v_mfma_f32_16x16x32_bf16 v[122:125], v[142:145], v[172:175], v[122:125]
	v_mfma_f32_16x16x32_bf16 v[110:113], v[134:137], v[180:183], v[110:113]
	v_mfma_f32_16x16x32_bf16 v[106:109], v[142:145], v[180:183], v[106:109]
	v_mfma_f32_16x16x32_bf16 v[94:97], v[134:137], v[188:191], v[94:97]
	v_mfma_f32_16x16x32_bf16 v[90:93], v[142:145], v[188:191], v[90:93]
	v_mfma_f32_16x16x32_bf16 v[78:81], v[134:137], v[200:203], v[78:81]
	v_mfma_f32_16x16x32_bf16 v[74:77], v[142:145], v[200:203], v[74:77]
	v_mfma_f32_16x16x32_bf16 v[118:121], v[146:149], v[168:171], v[118:121]
	v_mfma_f32_16x16x32_bf16 v[114:117], v[154:157], v[168:171], v[114:117]
	v_mfma_f32_16x16x32_bf16 v[102:105], v[146:149], v[176:179], v[102:105]
	v_mfma_f32_16x16x32_bf16 v[98:101], v[154:157], v[176:179], v[98:101]
	v_mfma_f32_16x16x32_bf16 v[86:89], v[146:149], v[184:187], v[86:89]
	v_mfma_f32_16x16x32_bf16 v[82:85], v[154:157], v[184:187], v[82:85]
	v_mfma_f32_16x16x32_bf16 v[70:73], v[146:149], v[192:195], v[70:73]
	v_mfma_f32_16x16x32_bf16 v[66:69], v[154:157], v[192:195], v[66:69]
	v_mfma_f32_16x16x32_bf16 v[118:121], v[150:153], v[172:175], v[118:121]
	v_mfma_f32_16x16x32_bf16 v[114:117], v[164:167], v[172:175], v[114:117]
	v_mfma_f32_16x16x32_bf16 v[102:105], v[150:153], v[180:183], v[102:105]
	v_mfma_f32_16x16x32_bf16 v[98:101], v[164:167], v[180:183], v[98:101]
	v_mfma_f32_16x16x32_bf16 v[86:89], v[150:153], v[188:191], v[86:89]
	v_mfma_f32_16x16x32_bf16 v[82:85], v[164:167], v[188:191], v[82:85]
	v_mfma_f32_16x16x32_bf16 v[70:73], v[150:153], v[200:203], v[70:73]
	v_mfma_f32_16x16x32_bf16 v[66:69], v[164:167], v[200:203], v[66:69]
	s_barrier
	s_setprio 0
	s_add_i32 s16, s2, 0xfff40080
	s_cmp_eq_u32 s61, 40
	s_cselect_b32 s64, s57, s16
	s_cselect_b32 s17, s35, s9
	s_cselect_b32 s16, s34, s8
	s_cselect_b32 s19, s51, s53
	s_cselect_b32 s18, s50, s52
	s_cselect_b32 s62, s58, s3
	s_cselect_b32 s20, s10, s12
	s_cselect_b32 s21, s11, s13
	s_cselect_b32 s22, s30, s14
	s_cselect_b32 s23, s31, s15
	s_or_b32 s63, s64, 0x80
	s_mov_b32 m0, s92
	ds_read_b128 v[168:171], v162 offset:16384
	ds_read_b128 v[172:175], v162 offset:17408
	ds_read_b128 v[176:179], v162 offset:18432
	ds_read_b128 v[180:183], v162 offset:19456
	ds_read_b128 v[184:187], v162 offset:20480
	ds_read_b128 v[188:191], v162 offset:21504
	ds_read_b128 v[192:195], v162 offset:22528
	ds_read_b128 v[200:203], v162 offset:23552
	v_add_u32_e32 v196, 0x1c000, v161
	ds_read_b128 v[206:209], v196
	ds_read_b128 v[210:213], v196 offset:1024
	ds_read_b128 v[214:217], v196 offset:2048
	ds_read_b128 v[218:221], v196 offset:3072
	buffer_load_dwordx4 v158, s[16:19], s62 offen lds
	s_mov_b32 m0, s93
	s_add_i32 s65, s62, 0xb0000
	buffer_load_dwordx4 v160, s[16:19], s62 offen lds
	s_mov_b32 m0, s94
	s_nop 0
	buffer_load_dwordx4 v158, s[16:19], s65 offen lds
	s_mov_b32 m0, s95
	s_nop 0
	buffer_load_dwordx4 v160, s[16:19], s65 offen lds
	s_waitcnt vmcnt(6)
	s_waitcnt lgkmcnt(0)
	s_setprio 1
	s_barrier
	v_mfma_f32_16x16x32_bf16 v[62:65], v[130:133], v[168:171], v[62:65]
	v_mfma_f32_16x16x32_bf16 v[58:61], v[138:141], v[168:171], v[58:61]
	v_mfma_f32_16x16x32_bf16 v[46:49], v[130:133], v[176:179], v[46:49]
	v_mfma_f32_16x16x32_bf16 v[42:45], v[138:141], v[176:179], v[42:45]
	v_mfma_f32_16x16x32_bf16 v[30:33], v[130:133], v[184:187], v[30:33]
	v_mfma_f32_16x16x32_bf16 v[26:29], v[138:141], v[184:187], v[26:29]
	v_mfma_f32_16x16x32_bf16 v[14:17], v[130:133], v[192:195], v[14:17]
	v_mfma_f32_16x16x32_bf16 v[10:13], v[138:141], v[192:195], v[10:13]
	v_mfma_f32_16x16x32_bf16 v[62:65], v[134:137], v[172:175], v[62:65]
	v_mfma_f32_16x16x32_bf16 v[58:61], v[142:145], v[172:175], v[58:61]
	v_mfma_f32_16x16x32_bf16 v[46:49], v[134:137], v[180:183], v[46:49]
	v_mfma_f32_16x16x32_bf16 v[42:45], v[142:145], v[180:183], v[42:45]
	v_mfma_f32_16x16x32_bf16 v[30:33], v[134:137], v[188:191], v[30:33]
	v_mfma_f32_16x16x32_bf16 v[26:29], v[142:145], v[188:191], v[26:29]
	v_mfma_f32_16x16x32_bf16 v[14:17], v[134:137], v[200:203], v[14:17]
	v_mfma_f32_16x16x32_bf16 v[10:13], v[142:145], v[200:203], v[10:13]
	v_mfma_f32_16x16x32_bf16 v[54:57], v[146:149], v[168:171], v[54:57]
	v_mfma_f32_16x16x32_bf16 v[50:53], v[154:157], v[168:171], v[50:53]
	v_mfma_f32_16x16x32_bf16 v[38:41], v[146:149], v[176:179], v[38:41]
	v_mfma_f32_16x16x32_bf16 v[34:37], v[154:157], v[176:179], v[34:37]
	v_mfma_f32_16x16x32_bf16 v[22:25], v[146:149], v[184:187], v[22:25]
	v_mfma_f32_16x16x32_bf16 v[18:21], v[154:157], v[184:187], v[18:21]
	v_mfma_f32_16x16x32_bf16 v[6:9], v[146:149], v[192:195], v[6:9]
	v_mfma_f32_16x16x32_bf16 v[2:5], v[154:157], v[192:195], v[2:5]
	v_mfma_f32_16x16x32_bf16 v[54:57], v[150:153], v[172:175], v[54:57]
	v_mfma_f32_16x16x32_bf16 v[50:53], v[164:167], v[172:175], v[50:53]
	v_mfma_f32_16x16x32_bf16 v[38:41], v[150:153], v[180:183], v[38:41]
	v_mfma_f32_16x16x32_bf16 v[34:37], v[164:167], v[180:183], v[34:37]
	v_mfma_f32_16x16x32_bf16 v[22:25], v[150:153], v[188:191], v[22:25]
	v_mfma_f32_16x16x32_bf16 v[18:21], v[164:167], v[188:191], v[18:21]
	v_mfma_f32_16x16x32_bf16 v[6:9], v[150:153], v[200:203], v[6:9]
	v_mfma_f32_16x16x32_bf16 v[2:5], v[164:167], v[200:203], v[2:5]
	s_barrier
	s_setprio 0
	s_mov_b32 m0, s44
	s_nop 0
	buffer_load_dwordx4 v0, s[20:23], s64 offen lds
	s_mov_b32 m0, s36
	s_nop 0
	buffer_load_dwordx4 v159, s[20:23], s64 offen lds
	v_add_u32_e32 v142, 0x18000, v161
	v_add_u32_e32 v163, 0x1c000, v161
	ds_read_b128 v[130:133], v142
	ds_read_b128 v[134:137], v142 offset:1024
	ds_read_b128 v[138:141], v142 offset:2048
	ds_read_b128 v[142:145], v142 offset:3072
	s_add_i32 s64, s64, 0xc0000
	s_mov_b32 m0, s37
	ds_read_b128 v[168:171], v162 offset:32768
	ds_read_b128 v[172:175], v162 offset:33792
	ds_read_b128 v[176:179], v162 offset:34816
	ds_read_b128 v[180:183], v162 offset:35840
	ds_read_b128 v[184:187], v162 offset:36864
	ds_read_b128 v[188:191], v162 offset:37888
	ds_read_b128 v[192:195], v162 offset:38912
	ds_read_b128 v[200:203], v162 offset:39936
	buffer_load_dwordx4 v0, s[20:23], s64 offen lds
	s_mov_b32 m0, s38
	s_nop 0
	buffer_load_dwordx4 v159, s[20:23], s64 offen lds
	s_waitcnt vmcnt(8)
	s_waitcnt lgkmcnt(0)
	s_setprio 1
	s_barrier
	v_mfma_f32_16x16x32_bf16 v[126:129], v[130:133], v[168:171], v[126:129]
	v_mfma_f32_16x16x32_bf16 v[122:125], v[138:141], v[168:171], v[122:125]
	v_mfma_f32_16x16x32_bf16 v[110:113], v[130:133], v[176:179], v[110:113]
	v_mfma_f32_16x16x32_bf16 v[106:109], v[138:141], v[176:179], v[106:109]
	v_mfma_f32_16x16x32_bf16 v[94:97], v[130:133], v[184:187], v[94:97]
	v_mfma_f32_16x16x32_bf16 v[90:93], v[138:141], v[184:187], v[90:93]
	v_mfma_f32_16x16x32_bf16 v[78:81], v[130:133], v[192:195], v[78:81]
	v_mfma_f32_16x16x32_bf16 v[74:77], v[138:141], v[192:195], v[74:77]
	v_mfma_f32_16x16x32_bf16 v[126:129], v[134:137], v[172:175], v[126:129]
	v_mfma_f32_16x16x32_bf16 v[122:125], v[142:145], v[172:175], v[122:125]
	v_mfma_f32_16x16x32_bf16 v[110:113], v[134:137], v[180:183], v[110:113]
	v_mfma_f32_16x16x32_bf16 v[106:109], v[142:145], v[180:183], v[106:109]
	v_mfma_f32_16x16x32_bf16 v[94:97], v[134:137], v[188:191], v[94:97]
	v_mfma_f32_16x16x32_bf16 v[90:93], v[142:145], v[188:191], v[90:93]
	v_mfma_f32_16x16x32_bf16 v[78:81], v[134:137], v[200:203], v[78:81]
	v_mfma_f32_16x16x32_bf16 v[74:77], v[142:145], v[200:203], v[74:77]
	v_mfma_f32_16x16x32_bf16 v[118:121], v[206:209], v[168:171], v[118:121]
	v_mfma_f32_16x16x32_bf16 v[114:117], v[214:217], v[168:171], v[114:117]
	v_mfma_f32_16x16x32_bf16 v[102:105], v[206:209], v[176:179], v[102:105]
	v_mfma_f32_16x16x32_bf16 v[98:101], v[214:217], v[176:179], v[98:101]
	v_mfma_f32_16x16x32_bf16 v[86:89], v[206:209], v[184:187], v[86:89]
	v_mfma_f32_16x16x32_bf16 v[82:85], v[214:217], v[184:187], v[82:85]
	v_mfma_f32_16x16x32_bf16 v[70:73], v[206:209], v[192:195], v[70:73]
	v_mfma_f32_16x16x32_bf16 v[66:69], v[214:217], v[192:195], v[66:69]
	v_mfma_f32_16x16x32_bf16 v[118:121], v[210:213], v[172:175], v[118:121]
	v_mfma_f32_16x16x32_bf16 v[114:117], v[218:221], v[172:175], v[114:117]
	v_mfma_f32_16x16x32_bf16 v[102:105], v[210:213], v[180:183], v[102:105]
	v_mfma_f32_16x16x32_bf16 v[98:101], v[218:221], v[180:183], v[98:101]
	v_mfma_f32_16x16x32_bf16 v[86:89], v[210:213], v[188:191], v[86:89]
	v_mfma_f32_16x16x32_bf16 v[82:85], v[218:221], v[188:191], v[82:85]
	v_mfma_f32_16x16x32_bf16 v[70:73], v[210:213], v[200:203], v[70:73]
	v_mfma_f32_16x16x32_bf16 v[66:69], v[218:221], v[200:203], v[66:69]
	s_barrier
; #define PG8_STAGE(bufoff, gbase, voff) do { const Src _g = (gbase); _Pragma("unroll") for (int _i = 0; _i < 2; ++_i) \
;         __builtin_amdgcn_raw_ptr_buffer_load_lds(_g.r, (LAS unsigned*)(lds + (bufoff) + ldsw + _i * 8192), 16, (voff)[_i], _g.o, 0, 0); } while (0)
; #define PG8_WAIT_V(n) asm volatile("s_waitcnt vmcnt(" #n ")" ::: "memory")
; template <class Epi, bool ALIGN_EPI, bool SP2, class Hook>
; __device__ __forceinline__ void gemm_phase(LAS unsigned char* lds, const Gemm g, const StaticOrder& S, const Epi& E, Acc& acc, const bool fresh, const Hook& H, const int wave_id) {
;     ...
;         for (int t = t0; t < nt; t += 2) {
;             const bool last = (t == nt - 2);
;             const Src a1 = cA + (size_t)(t + 1) * kstep;
;             const Src a2 = last ? nA : cA + (size_t)(t + 2) * kstep, b2 = last ? nB : cB + (size_t)(t + 2) * kstep;
;             const Src a3 = a2 + kstep, b3 = b2 + kstep;
;             if (last && has_next) H(nxt);
;             if constexpr (SP2) {
;             PG8_TRIP_SP2(PG8_WAIT_V(8));
;             } else {
;             PG8_LDB(B0, 0, 0); PG8_SCHED; PG8_LDA(At, 0, 0); PG8_STAGE(PG8_SA(1, 1), a1 + hstepA, voffA);
;             PG8_WAIT_L(8); PG8_BAR; PG8_WAIT_L(0); PG8_MMA(0, 0, At, B0); PG8_BAR; PG8_SCHED;
;             PG8_LDB(B1, 0, 1); PG8_STAGE(PG8_SB(0, 0), b2, voffB);
;             PG8_BAR; PG8_WAIT_L(0); PG8_MMA(0, 1, At, B1); PG8_BAR;
;             PG8_LDA(At, 0, 1); PG8_STAGE(PG8_SA(0, 0), a2, voffA);
;             PG8_BAR; PG8_WAIT_L(0); PG8_MMA(1, 0, At, B0); PG8_BAR; PG8_SCHED;
;             PG8_STAGE(PG8_SB(0, 1), b2 + hstep, voffB);
;             PG8_WAIT_V(6); PG8_BAR; PG8_MMA(1, 1, At, B1); PG8_BAR;
;             PG8_LDB(B0, 1, 0); PG8_SCHED; PG8_LDA(At, 1, 0); PG8_STAGE(PG8_SA(0, 1), a2 + hstepA, voffA);
;             PG8_WAIT_L(8); PG8_BAR; PG8_WAIT_L(0); PG8_MMA(0, 0, At, B0); PG8_BAR; PG8_SCHED;
;             PG8_LDB(B1, 1, 1); PG8_STAGE(PG8_SB(1, 0), b3, voffB);
;             PG8_BAR; PG8_WAIT_L(0); PG8_MMA(0, 1, At, B1); PG8_BAR;
;             PG8_LDA(At, 1, 1); PG8_STAGE(PG8_SA(1, 0), a3, voffA);
;             PG8_BAR; PG8_WAIT_L(0); PG8_MMA(1, 0, At, B0); PG8_BAR; PG8_SCHED;
;             PG8_STAGE(PG8_SB(1, 1), b3 + hstep, voffB);
;             PG8_WAIT_V(6); PG8_BAR; PG8_MMA(1, 1, At, B1); PG8_BAR;
;             }
;         }
;         if constexpr (ALIGN_EPI) { if (wr == 0) PG8_BAR; }
	s_setprio 0
	s_mov_b32 m0, s39
	s_or_b32 s64, s62, 0x80
	ds_read_b128 v[168:171], v162 offset:49152
	ds_read_b128 v[172:175], v162 offset:50176
	ds_read_b128 v[176:179], v162 offset:51200
	ds_read_b128 v[180:183], v162 offset:52224
	ds_read_b128 v[184:187], v162 offset:53248
	ds_read_b128 v[188:191], v162 offset:54272
	ds_read_b128 v[192:195], v162 offset:55296
	ds_read_b128 v[200:203], v162 offset:56320
	buffer_load_dwordx4 v158, s[16:19], s64 offen lds
	s_mov_b32 m0, s40
	s_add_i32 s62, s62, 0xb0080
	buffer_load_dwordx4 v160, s[16:19], s64 offen lds
	s_mov_b32 m0, s43
	s_nop 0
	buffer_load_dwordx4 v158, s[16:19], s62 offen lds
	s_mov_b32 m0, s42
	s_nop 0
	buffer_load_dwordx4 v160, s[16:19], s62 offen lds
	s_waitcnt vmcnt(6)
	s_waitcnt lgkmcnt(0)
	s_setprio 1
	s_barrier
	v_mfma_f32_16x16x32_bf16 v[62:65], v[130:133], v[168:171], v[62:65]
	v_mfma_f32_16x16x32_bf16 v[58:61], v[138:141], v[168:171], v[58:61]
	v_mfma_f32_16x16x32_bf16 v[46:49], v[130:133], v[176:179], v[46:49]
	v_mfma_f32_16x16x32_bf16 v[42:45], v[138:141], v[176:179], v[42:45]
	v_mfma_f32_16x16x32_bf16 v[30:33], v[130:133], v[184:187], v[30:33]
	v_mfma_f32_16x16x32_bf16 v[26:29], v[138:141], v[184:187], v[26:29]
	v_mfma_f32_16x16x32_bf16 v[14:17], v[130:133], v[192:195], v[14:17]
	v_mfma_f32_16x16x32_bf16 v[10:13], v[138:141], v[192:195], v[10:13]
	v_mfma_f32_16x16x32_bf16 v[62:65], v[134:137], v[172:175], v[62:65]
	v_mfma_f32_16x16x32_bf16 v[58:61], v[142:145], v[172:175], v[58:61]
	v_mfma_f32_16x16x32_bf16 v[46:49], v[134:137], v[180:183], v[46:49]
	v_mfma_f32_16x16x32_bf16 v[42:45], v[142:145], v[180:183], v[42:45]
	v_mfma_f32_16x16x32_bf16 v[30:33], v[134:137], v[188:191], v[30:33]
	v_mfma_f32_16x16x32_bf16 v[26:29], v[142:145], v[188:191], v[26:29]
	v_mfma_f32_16x16x32_bf16 v[14:17], v[134:137], v[200:203], v[14:17]
	v_mfma_f32_16x16x32_bf16 v[10:13], v[142:145], v[200:203], v[10:13]
	v_mfma_f32_16x16x32_bf16 v[54:57], v[206:209], v[168:171], v[54:57]
	v_mfma_f32_16x16x32_bf16 v[50:53], v[214:217], v[168:171], v[50:53]
	v_mfma_f32_16x16x32_bf16 v[38:41], v[206:209], v[176:179], v[38:41]
	v_mfma_f32_16x16x32_bf16 v[34:37], v[214:217], v[176:179], v[34:37]
	v_mfma_f32_16x16x32_bf16 v[22:25], v[206:209], v[184:187], v[22:25]
	v_mfma_f32_16x16x32_bf16 v[18:21], v[214:217], v[184:187], v[18:21]
	v_mfma_f32_16x16x32_bf16 v[6:9], v[206:209], v[192:195], v[6:9]
	v_mfma_f32_16x16x32_bf16 v[2:5], v[214:217], v[192:195], v[2:5]
	v_mfma_f32_16x16x32_bf16 v[54:57], v[210:213], v[172:175], v[54:57]
	v_mfma_f32_16x16x32_bf16 v[50:53], v[218:221], v[172:175], v[50:53]
	v_mfma_f32_16x16x32_bf16 v[38:41], v[210:213], v[180:183], v[38:41]
	v_mfma_f32_16x16x32_bf16 v[34:37], v[218:221], v[180:183], v[34:37]
	v_mfma_f32_16x16x32_bf16 v[22:25], v[210:213], v[188:191], v[22:25]
	v_mfma_f32_16x16x32_bf16 v[18:21], v[218:221], v[188:191], v[18:21]
	v_mfma_f32_16x16x32_bf16 v[6:9], v[210:213], v[200:203], v[6:9]
	v_mfma_f32_16x16x32_bf16 v[2:5], v[218:221], v[200:203], v[2:5]
	s_barrier
	s_setprio 0
	s_add_i32 s61, s61, 2
	s_addk_i32 s2, 0x100
	s_addk_i32 s3, 0x100
	s_cmp_gt_u32 s61, 41
	s_cbranch_scc0 .LBB0_1572
	s_mov_b32 m0, s41
	s_nop 0
	buffer_load_dwordx4 v0, s[20:23], s63 offen lds
	s_mov_b32 m0, s33
	s_nop 0
	buffer_load_dwordx4 v159, s[20:23], s63 offen lds
	v_readlane_b32 s2, v251, 45
	v_readlane_b32 s3, v251, 46
	s_and_b64 vcc, exec, s[2:3]
	s_cbranch_vccz .LBB0_1575
	s_barrier

; #define PG8_WAIT_V(n) asm volatile("s_waitcnt vmcnt(" #n ")" ::: "memory")
; template <class Epi, bool ALIGN_EPI, bool SP2, class Hook>
; __device__ __forceinline__ void gemm_phase(LAS unsigned char* lds, const Gemm g, const StaticOrder& S, const Epi& E, Acc& acc, const bool fresh, const Hook& H, const int wave_id) {
;     ...
;         for (int t = t0; t < nt; t += 2) {
;             const bool last = (t == nt - 2);
;             const Src a1 = cA + (size_t)(t + 1) * kstep;
;             const Src a2 = last ? nA : cA + (size_t)(t + 2) * kstep, b2 = last ? nB : cB + (size_t)(t + 2) * kstep;
;             const Src a3 = a2 + kstep, b3 = b2 + kstep;
;             if (last && has_next) H(nxt);
;             if constexpr (SP2) {
;             PG8_TRIP_SP2(PG8_WAIT_V(8));
.LBB0_1614:
	s_add_i32 s100, s2, 0xfff40000
	v_add_u32_e32 v0, 0x10000, v172
	ds_read_b128 v[130:133], v0
	ds_read_b128 v[134:137], v0 offset:1024
	ds_read_b128 v[138:141], v0 offset:2048
	ds_read_b128 v[142:145], v0 offset:3072
	v_add_u32_e32 v0, 0x14000, v172
	ds_read_b128 v[146:149], v0
	ds_read_b128 v[150:153], v0 offset:1024
	ds_read_b128 v[154:157], v0 offset:2048
	ds_read_b128 v[158:161], v0 offset:3072
	s_mov_b32 m0, s41
	s_nop 0
	buffer_load_dwordx4 v168, s[8:11], s100 offen lds
	s_mov_b32 m0, s33
	s_nop 0
	buffer_load_dwordx4 v170, s[8:11], s100 offen lds
	s_mov_b32 m0, s45
	ds_read_b128 v[162:165], v173
	ds_read_b128 v[174:177], v173 offset:1024
	ds_read_b128 v[178:181], v173 offset:2048
	ds_read_b128 v[182:185], v173 offset:3072
	ds_read_b128 v[186:189], v173 offset:4096
	ds_read_b128 v[190:193], v173 offset:5120
	ds_read_b128 v[194:197], v173 offset:6144
	ds_read_b128 v[200:203], v173 offset:7168
	buffer_load_dwordx4 v168, s[8:11], s2 offen lds
	s_mov_b32 m0, s46
	s_nop 0
	buffer_load_dwordx4 v170, s[8:11], s2 offen lds
	s_waitcnt vmcnt(4)
	s_waitcnt lgkmcnt(0)
	s_setprio 1
	s_barrier
	v_mfma_f32_16x16x32_bf16 v[126:129], v[130:133], v[162:165], v[126:129]
	v_mfma_f32_16x16x32_bf16 v[122:125], v[138:141], v[162:165], v[122:125]
	v_mfma_f32_16x16x32_bf16 v[110:113], v[130:133], v[178:181], v[110:113]
	v_mfma_f32_16x16x32_bf16 v[106:109], v[138:141], v[178:181], v[106:109]
	v_mfma_f32_16x16x32_bf16 v[94:97], v[130:133], v[186:189], v[94:97]
	v_mfma_f32_16x16x32_bf16 v[90:93], v[138:141], v[186:189], v[90:93]
	v_mfma_f32_16x16x32_bf16 v[78:81], v[130:133], v[194:197], v[78:81]
	v_mfma_f32_16x16x32_bf16 v[74:77], v[138:141], v[194:197], v[74:77]
	v_mfma_f32_16x16x32_bf16 v[126:129], v[134:137], v[174:177], v[126:129]
	v_mfma_f32_16x16x32_bf16 v[122:125], v[142:145], v[174:177], v[122:125]
	v_mfma_f32_16x16x32_bf16 v[110:113], v[134:137], v[182:185], v[110:113]
	v_mfma_f32_16x16x32_bf16 v[106:109], v[142:145], v[182:185], v[106:109]
	v_mfma_f32_16x16x32_bf16 v[94:97], v[134:137], v[190:193], v[94:97]
	v_mfma_f32_16x16x32_bf16 v[90:93], v[142:145], v[190:193], v[90:93]
	v_mfma_f32_16x16x32_bf16 v[78:81], v[134:137], v[200:203], v[78:81]
	v_mfma_f32_16x16x32_bf16 v[74:77], v[142:145], v[200:203], v[74:77]
	v_mfma_f32_16x16x32_bf16 v[118:121], v[146:149], v[162:165], v[118:121]
	v_mfma_f32_16x16x32_bf16 v[114:117], v[154:157], v[162:165], v[114:117]
	v_mfma_f32_16x16x32_bf16 v[102:105], v[146:149], v[178:181], v[102:105]
	v_mfma_f32_16x16x32_bf16 v[98:101], v[154:157], v[178:181], v[98:101]
	v_mfma_f32_16x16x32_bf16 v[86:89], v[146:149], v[186:189], v[86:89]
	v_mfma_f32_16x16x32_bf16 v[82:85], v[154:157], v[186:189], v[82:85]
	v_mfma_f32_16x16x32_bf16 v[70:73], v[146:149], v[194:197], v[70:73]
	v_mfma_f32_16x16x32_bf16 v[66:69], v[154:157], v[194:197], v[66:69]
	v_mfma_f32_16x16x32_bf16 v[118:121], v[150:153], v[174:177], v[118:121]
	v_mfma_f32_16x16x32_bf16 v[114:117], v[158:161], v[174:177], v[114:117]
	v_mfma_f32_16x16x32_bf16 v[102:105], v[150:153], v[182:185], v[102:105]
	v_mfma_f32_16x16x32_bf16 v[98:101], v[158:161], v[182:185], v[98:101]
	v_mfma_f32_16x16x32_bf16 v[86:89], v[150:153], v[190:193], v[86:89]
	v_mfma_f32_16x16x32_bf16 v[82:85], v[158:161], v[190:193], v[82:85]
	v_mfma_f32_16x16x32_bf16 v[70:73], v[150:153], v[200:203], v[70:73]
	v_mfma_f32_16x16x32_bf16 v[66:69], v[158:161], v[200:203], v[66:69]
	s_barrier
	s_setprio 0
	s_add_i32 s12, s2, 0xfff40080
	s_cmp_eq_u32 s59, 40
	s_cselect_b32 s62, s55, s12
	s_cselect_b32 s13, s31, s77
	s_cselect_b32 s12, s30, s76
	s_cselect_b32 s15, s35, s51
	s_cselect_b32 s14, s34, s50
	s_cselect_b32 s60, s56, s3
	s_cselect_b32 s16, s20, s8
	s_cselect_b32 s17, s21, s9
	s_cselect_b32 s18, s22, s10
	s_cselect_b32 s19, s23, s11
	s_or_b32 s61, s62, 0x80
	s_mov_b32 m0, s92
	ds_read_b128 v[162:165], v173 offset:16384
	ds_read_b128 v[174:177], v173 offset:17408
	ds_read_b128 v[178:181], v173 offset:18432
	ds_read_b128 v[182:185], v173 offset:19456
	ds_read_b128 v[186:189], v173 offset:20480
	ds_read_b128 v[190:193], v173 offset:21504
	ds_read_b128 v[194:197], v173 offset:22528
	ds_read_b128 v[200:203], v173 offset:23552
	v_add_u32_e32 v166, 0x1c000, v172
	ds_read_b128 v[206:209], v166
	ds_read_b128 v[210:213], v166 offset:1024
	ds_read_b128 v[214:217], v166 offset:2048
	ds_read_b128 v[218:221], v166 offset:3072
	buffer_load_dwordx4 v169, s[12:15], s60 offen lds
	s_mov_b32 m0, s93
	s_add_i32 s63, s60, 0xb0000
	buffer_load_dwordx4 v171, s[12:15], s60 offen lds
	s_mov_b32 m0, s94
	s_nop 0
	buffer_load_dwordx4 v169, s[12:15], s63 offen lds
	s_mov_b32 m0, s95
	s_nop 0
	buffer_load_dwordx4 v171, s[12:15], s63 offen lds
	s_waitcnt vmcnt(6)
	s_waitcnt lgkmcnt(0)
	s_setprio 1
	s_barrier
	v_mfma_f32_16x16x32_bf16 v[62:65], v[130:133], v[162:165], v[62:65]
	v_mfma_f32_16x16x32_bf16 v[58:61], v[138:141], v[162:165], v[58:61]
	v_mfma_f32_16x16x32_bf16 v[46:49], v[130:133], v[178:181], v[46:49]
	v_mfma_f32_16x16x32_bf16 v[42:45], v[138:141], v[178:181], v[42:45]
	v_mfma_f32_16x16x32_bf16 v[30:33], v[130:133], v[186:189], v[30:33]
	v_mfma_f32_16x16x32_bf16 v[26:29], v[138:141], v[186:189], v[26:29]
	v_mfma_f32_16x16x32_bf16 v[14:17], v[130:133], v[194:197], v[14:17]
	v_mfma_f32_16x16x32_bf16 v[10:13], v[138:141], v[194:197], v[10:13]
	v_mfma_f32_16x16x32_bf16 v[62:65], v[134:137], v[174:177], v[62:65]
	v_mfma_f32_16x16x32_bf16 v[58:61], v[142:145], v[174:177], v[58:61]
	v_mfma_f32_16x16x32_bf16 v[46:49], v[134:137], v[182:185], v[46:49]
	v_mfma_f32_16x16x32_bf16 v[42:45], v[142:145], v[182:185], v[42:45]
	v_mfma_f32_16x16x32_bf16 v[30:33], v[134:137], v[190:193], v[30:33]
	v_mfma_f32_16x16x32_bf16 v[26:29], v[142:145], v[190:193], v[26:29]
	v_mfma_f32_16x16x32_bf16 v[14:17], v[134:137], v[200:203], v[14:17]
	v_mfma_f32_16x16x32_bf16 v[10:13], v[142:145], v[200:203], v[10:13]
	v_mfma_f32_16x16x32_bf16 v[54:57], v[146:149], v[162:165], v[54:57]
	v_mfma_f32_16x16x32_bf16 v[50:53], v[154:157], v[162:165], v[50:53]
	v_mfma_f32_16x16x32_bf16 v[38:41], v[146:149], v[178:181], v[38:41]
	v_mfma_f32_16x16x32_bf16 v[34:37], v[154:157], v[178:181], v[34:37]
	v_mfma_f32_16x16x32_bf16 v[22:25], v[146:149], v[186:189], v[22:25]
	v_mfma_f32_16x16x32_bf16 v[18:21], v[154:157], v[186:189], v[18:21]
	v_mfma_f32_16x16x32_bf16 v[6:9], v[146:149], v[194:197], v[6:9]
	v_mfma_f32_16x16x32_bf16 v[2:5], v[154:157], v[194:197], v[2:5]
	v_mfma_f32_16x16x32_bf16 v[54:57], v[150:153], v[174:177], v[54:57]
	v_mfma_f32_16x16x32_bf16 v[50:53], v[158:161], v[174:177], v[50:53]
	v_mfma_f32_16x16x32_bf16 v[38:41], v[150:153], v[182:185], v[38:41]
	v_mfma_f32_16x16x32_bf16 v[34:37], v[158:161], v[182:185], v[34:37]
	v_mfma_f32_16x16x32_bf16 v[22:25], v[150:153], v[190:193], v[22:25]
	v_mfma_f32_16x16x32_bf16 v[18:21], v[158:161], v[190:193], v[18:21]
	v_mfma_f32_16x16x32_bf16 v[6:9], v[150:153], v[200:203], v[6:9]
	v_mfma_f32_16x16x32_bf16 v[2:5], v[158:161], v[200:203], v[2:5]
	s_barrier
	s_setprio 0
	s_mov_b32 m0, s44
	s_nop 0
	buffer_load_dwordx4 v168, s[16:19], s62 offen lds
	s_mov_b32 m0, s36
	s_nop 0
	buffer_load_dwordx4 v170, s[16:19], s62 offen lds
	v_add_u32_e32 v0, 0x18000, v172
	ds_read_b128 v[130:133], v0
	ds_read_b128 v[134:137], v0 offset:1024
	ds_read_b128 v[138:141], v0 offset:2048
	ds_read_b128 v[142:145], v0 offset:3072
	v_add_u32_e32 v0, 0x1c000, v172
	s_add_i32 s62, s62, 0xc0000
	s_mov_b32 m0, s37
	ds_read_b128 v[162:165], v173 offset:32768
	ds_read_b128 v[174:177], v173 offset:33792
	ds_read_b128 v[178:181], v173 offset:34816
	ds_read_b128 v[182:185], v173 offset:35840
	ds_read_b128 v[186:189], v173 offset:36864
	ds_read_b128 v[190:193], v173 offset:37888
	ds_read_b128 v[194:197], v173 offset:38912
	ds_read_b128 v[200:203], v173 offset:39936
	buffer_load_dwordx4 v168, s[16:19], s62 offen lds
	s_mov_b32 m0, s38
	s_nop 0
	buffer_load_dwordx4 v170, s[16:19], s62 offen lds
	s_waitcnt vmcnt(8)
	s_waitcnt lgkmcnt(0)
	s_setprio 1
	s_barrier
	v_mfma_f32_16x16x32_bf16 v[126:129], v[130:133], v[162:165], v[126:129]
	v_mfma_f32_16x16x32_bf16 v[122:125], v[138:141], v[162:165], v[122:125]
	v_mfma_f32_16x16x32_bf16 v[110:113], v[130:133], v[178:181], v[110:113]
	v_mfma_f32_16x16x32_bf16 v[106:109], v[138:141], v[178:181], v[106:109]
	v_mfma_f32_16x16x32_bf16 v[94:97], v[130:133], v[186:189], v[94:97]
	v_mfma_f32_16x16x32_bf16 v[90:93], v[138:141], v[186:189], v[90:93]
	v_mfma_f32_16x16x32_bf16 v[78:81], v[130:133], v[194:197], v[78:81]
	v_mfma_f32_16x16x32_bf16 v[74:77], v[138:141], v[194:197], v[74:77]
	v_mfma_f32_16x16x32_bf16 v[126:129], v[134:137], v[174:177], v[126:129]
	v_mfma_f32_16x16x32_bf16 v[122:125], v[142:145], v[174:177], v[122:125]
	v_mfma_f32_16x16x32_bf16 v[110:113], v[134:137], v[182:185], v[110:113]
	v_mfma_f32_16x16x32_bf16 v[106:109], v[142:145], v[182:185], v[106:109]
	v_mfma_f32_16x16x32_bf16 v[94:97], v[134:137], v[190:193], v[94:97]
	v_mfma_f32_16x16x32_bf16 v[90:93], v[142:145], v[190:193], v[90:93]
	v_mfma_f32_16x16x32_bf16 v[78:81], v[134:137], v[200:203], v[78:81]
	v_mfma_f32_16x16x32_bf16 v[74:77], v[142:145], v[200:203], v[74:77]
	v_mfma_f32_16x16x32_bf16 v[118:121], v[206:209], v[162:165], v[118:121]
	v_mfma_f32_16x16x32_bf16 v[114:117], v[214:217], v[162:165], v[114:117]
	v_mfma_f32_16x16x32_bf16 v[102:105], v[206:209], v[178:181], v[102:105]
	v_mfma_f32_16x16x32_bf16 v[98:101], v[214:217], v[178:181], v[98:101]
	v_mfma_f32_16x16x32_bf16 v[86:89], v[206:209], v[186:189], v[86:89]
	v_mfma_f32_16x16x32_bf16 v[82:85], v[214:217], v[186:189], v[82:85]
	v_mfma_f32_16x16x32_bf16 v[70:73], v[206:209], v[194:197], v[70:73]
	v_mfma_f32_16x16x32_bf16 v[66:69], v[214:217], v[194:197], v[66:69]
	v_mfma_f32_16x16x32_bf16 v[118:121], v[210:213], v[174:177], v[118:121]
	v_mfma_f32_16x16x32_bf16 v[114:117], v[218:221], v[174:177], v[114:117]
	v_mfma_f32_16x16x32_bf16 v[102:105], v[210:213], v[182:185], v[102:105]
	v_mfma_f32_16x16x32_bf16 v[98:101], v[218:221], v[182:185], v[98:101]
	v_mfma_f32_16x16x32_bf16 v[86:89], v[210:213], v[190:193], v[86:89]
	v_mfma_f32_16x16x32_bf16 v[82:85], v[218:221], v[190:193], v[82:85]
	v_mfma_f32_16x16x32_bf16 v[70:73], v[210:213], v[200:203], v[70:73]
	v_mfma_f32_16x16x32_bf16 v[66:69], v[218:221], v[200:203], v[66:69]
	s_barrier
; #define PG8_STAGE(bufoff, gbase, voff) do { const Src _g = (gbase); _Pragma("unroll") for (int _i = 0; _i < 2; ++_i) \
;         __builtin_amdgcn_raw_ptr_buffer_load_lds(_g.r, (LAS unsigned*)(lds + (bufoff) + ldsw + _i * 8192), 16, (voff)[_i], _g.o, 0, 0); } while (0)
; #define PG8_WAIT_V(n) asm volatile("s_waitcnt vmcnt(" #n ")" ::: "memory")
; template <class Epi, bool ALIGN_EPI, bool SP2, class Hook>
; __device__ __forceinline__ void gemm_phase(LAS unsigned char* lds, const Gemm g, const StaticOrder& S, const Epi& E, Acc& acc, const bool fresh, const Hook& H, const int wave_id) {
;     ...
;         for (int t = t0; t < nt; t += 2) {
;             const bool last = (t == nt - 2);
;             const Src a1 = cA + (size_t)(t + 1) * kstep;
;             const Src a2 = last ? nA : cA + (size_t)(t + 2) * kstep, b2 = last ? nB : cB + (size_t)(t + 2) * kstep;
;             const Src a3 = a2 + kstep, b3 = b2 + kstep;
;             if (last && has_next) H(nxt);
;             if constexpr (SP2) {
;             PG8_TRIP_SP2(PG8_WAIT_V(8));
;             } else {
;             PG8_LDB(B0, 0, 0); PG8_SCHED; PG8_LDA(At, 0, 0); PG8_STAGE(PG8_SA(1, 1), a1 + hstepA, voffA);
;             PG8_WAIT_L(8); PG8_BAR; PG8_WAIT_L(0); PG8_MMA(0, 0, At, B0); PG8_BAR; PG8_SCHED;
;             PG8_LDB(B1, 0, 1); PG8_STAGE(PG8_SB(0, 0), b2, voffB);
;             PG8_BAR; PG8_WAIT_L(0); PG8_MMA(0, 1, At, B1); PG8_BAR;
;             PG8_LDA(At, 0, 1); PG8_STAGE(PG8_SA(0, 0), a2, voffA);
;             PG8_BAR; PG8_WAIT_L(0); PG8_MMA(1, 0, At, B0); PG8_BAR; PG8_SCHED;
;             PG8_STAGE(PG8_SB(0, 1), b2 + hstep, voffB);
;             PG8_WAIT_V(6); PG8_BAR; PG8_MMA(1, 1, At, B1); PG8_BAR;
;             PG8_LDB(B0, 1, 0); PG8_SCHED; PG8_LDA(At, 1, 0); PG8_STAGE(PG8_SA(0, 1), a2 + hstepA, voffA);
;             PG8_WAIT_L(8); PG8_BAR; PG8_WAIT_L(0); PG8_MMA(0, 0, At, B0); PG8_BAR; PG8_SCHED;
;             PG8_LDB(B1, 1, 1); PG8_STAGE(PG8_SB(1, 0), b3, voffB);
;             PG8_BAR; PG8_WAIT_L(0); PG8_MMA(0, 1, At, B1); PG8_BAR;
;             PG8_LDA(At, 1, 1); PG8_STAGE(PG8_SA(1, 0), a3, voffA);
;             PG8_BAR; PG8_WAIT_L(0); PG8_MMA(1, 0, At, B0); PG8_BAR; PG8_SCHED;
;             PG8_STAGE(PG8_SB(1, 1), b3 + hstep, voffB);
;             PG8_WAIT_V(6); PG8_BAR; PG8_MMA(1, 1, At, B1); PG8_BAR;
;             }
;         }
;         if constexpr (ALIGN_EPI) { if (wr == 0) PG8_BAR; }
	s_setprio 0
	s_mov_b32 m0, s39
	s_or_b32 s62, s60, 0x80
	ds_read_b128 v[162:165], v173 offset:49152
	ds_read_b128 v[174:177], v173 offset:50176
	ds_read_b128 v[178:181], v173 offset:51200
	ds_read_b128 v[182:185], v173 offset:52224
	ds_read_b128 v[186:189], v173 offset:53248
	ds_read_b128 v[190:193], v173 offset:54272
	ds_read_b128 v[194:197], v173 offset:55296
	ds_read_b128 v[200:203], v173 offset:56320
	buffer_load_dwordx4 v169, s[12:15], s62 offen lds
	s_mov_b32 m0, s40
	s_add_i32 s60, s60, 0xb0080
	buffer_load_dwordx4 v171, s[12:15], s62 offen lds
	s_mov_b32 m0, s43
	s_nop 0
	buffer_load_dwordx4 v169, s[12:15], s60 offen lds
	s_mov_b32 m0, s42
	s_nop 0
	buffer_load_dwordx4 v171, s[12:15], s60 offen lds
	s_waitcnt vmcnt(6)
	s_waitcnt lgkmcnt(0)
	s_setprio 1
	s_barrier
	v_mfma_f32_16x16x32_bf16 v[62:65], v[130:133], v[162:165], v[62:65]
	v_mfma_f32_16x16x32_bf16 v[58:61], v[138:141], v[162:165], v[58:61]
	v_mfma_f32_16x16x32_bf16 v[46:49], v[130:133], v[178:181], v[46:49]
	v_mfma_f32_16x16x32_bf16 v[42:45], v[138:141], v[178:181], v[42:45]
	v_mfma_f32_16x16x32_bf16 v[30:33], v[130:133], v[186:189], v[30:33]
	v_mfma_f32_16x16x32_bf16 v[26:29], v[138:141], v[186:189], v[26:29]
	v_mfma_f32_16x16x32_bf16 v[14:17], v[130:133], v[194:197], v[14:17]
	v_mfma_f32_16x16x32_bf16 v[10:13], v[138:141], v[194:197], v[10:13]
	v_mfma_f32_16x16x32_bf16 v[62:65], v[134:137], v[174:177], v[62:65]
	v_mfma_f32_16x16x32_bf16 v[58:61], v[142:145], v[174:177], v[58:61]
	v_mfma_f32_16x16x32_bf16 v[46:49], v[134:137], v[182:185], v[46:49]
	v_mfma_f32_16x16x32_bf16 v[42:45], v[142:145], v[182:185], v[42:45]
	v_mfma_f32_16x16x32_bf16 v[30:33], v[134:137], v[190:193], v[30:33]
	v_mfma_f32_16x16x32_bf16 v[26:29], v[142:145], v[190:193], v[26:29]
	v_mfma_f32_16x16x32_bf16 v[14:17], v[134:137], v[200:203], v[14:17]
	v_mfma_f32_16x16x32_bf16 v[10:13], v[142:145], v[200:203], v[10:13]
	v_mfma_f32_16x16x32_bf16 v[54:57], v[206:209], v[162:165], v[54:57]
	v_mfma_f32_16x16x32_bf16 v[50:53], v[214:217], v[162:165], v[50:53]
	v_mfma_f32_16x16x32_bf16 v[38:41], v[206:209], v[178:181], v[38:41]
	v_mfma_f32_16x16x32_bf16 v[34:37], v[214:217], v[178:181], v[34:37]
	v_mfma_f32_16x16x32_bf16 v[22:25], v[206:209], v[186:189], v[22:25]
	v_mfma_f32_16x16x32_bf16 v[18:21], v[214:217], v[186:189], v[18:21]
	v_mfma_f32_16x16x32_bf16 v[6:9], v[206:209], v[194:197], v[6:9]
	v_mfma_f32_16x16x32_bf16 v[2:5], v[214:217], v[194:197], v[2:5]
	v_mfma_f32_16x16x32_bf16 v[54:57], v[210:213], v[174:177], v[54:57]
	v_mfma_f32_16x16x32_bf16 v[50:53], v[218:221], v[174:177], v[50:53]
	v_mfma_f32_16x16x32_bf16 v[38:41], v[210:213], v[182:185], v[38:41]
	v_mfma_f32_16x16x32_bf16 v[34:37], v[218:221], v[182:185], v[34:37]
	v_mfma_f32_16x16x32_bf16 v[22:25], v[210:213], v[190:193], v[22:25]
	v_mfma_f32_16x16x32_bf16 v[18:21], v[218:221], v[190:193], v[18:21]
	v_mfma_f32_16x16x32_bf16 v[6:9], v[210:213], v[200:203], v[6:9]
	v_mfma_f32_16x16x32_bf16 v[2:5], v[218:221], v[200:203], v[2:5]
	s_barrier
	s_setprio 0
	s_add_i32 s59, s59, 2
	s_addk_i32 s2, 0x100
	s_addk_i32 s3, 0x100
	s_cmp_gt_u32 s59, 41
	s_cbranch_scc0 .LBB0_1614
	s_mov_b32 m0, s41
	s_nop 0
	buffer_load_dwordx4 v168, s[16:19], s61 offen lds
	s_mov_b32 m0, s33
	s_nop 0
	buffer_load_dwordx4 v170, s[16:19], s61 offen lds
	v_readlane_b32 s2, v251, 45
	v_readlane_b32 s3, v251, 46
	s_and_b64 vcc, exec, s[2:3]
	s_cbranch_vccz .LBB0_1617
	s_barrier
